# strategy 9 loop-edge rotation: K-loop pointer/counter scalar ops issued in the last MFMA block's shadow, back edge skips the head block; on stack20
# speedup vs baseline: 1.0012x; 1.0012x over previous
; #define PG8_STAGE(bufoff, gbase, voff) do { _Pragma("unroll") for (int _i = 0; _i < 2; ++_i) \
;         __builtin_amdgcn_global_load_lds((const unsigned*)((const char*)(gbase) + (voff)[_i]), (PG8_LAS unsigned*)(lds + (bufoff) + ldsw + _i * 8192), 16, 0, 0); } while (0)
; #define PG8_LDA(dst, b, h) do { _Pragma("unroll") for (int m = 0; m < 4; ++m) _Pragma("unroll") for (int k = 0; k < 2; ++k) dst[m][k] = *(const PG8_LAS bf16x8*)(lds + PG8_SA(b, h) + aoff + m * 2048 + k * 1024); } while (0)
; #define PG8_LDB(dst, b, h) do { _Pragma("unroll") for (int n = 0; n < 2; ++n) _Pragma("unroll") for (int k = 0; k < 2; ++k) dst[n][k] = *(const PG8_LAS bf16x8*)(lds + PG8_SB(b, h) + boff + n * 2048 + k * 1024); } while (0)
; #define PG8_MMA(ai, bj, At, Bt) do { __builtin_amdgcn_s_setprio(1); _Pragma("unroll") for (int m = 0; m < 4; ++m) _Pragma("unroll") for (int n = 0; n < 2; ++n) _Pragma("unroll") for (int k = 0; k < 2; ++k) \
;         acc[ai][bj][m][n] = __builtin_amdgcn_mfma_f32_16x16x32_bf16(Bt[n][k], At[m][k], acc[ai][bj][m][n], 0, 0, 0); __builtin_amdgcn_s_setprio(0); } while (0)
; #define PG8_WAIT_V(n) asm volatile("s_waitcnt vmcnt(" #n ")" ::: "memory")
; #define PG8_WAIT_L(n) asm volatile("s_waitcnt lgkmcnt(" #n ")" ::: "memory")
; #define PG8_BAR __builtin_amdgcn_s_barrier()
; #define PG8_SCHED __builtin_amdgcn_sched_barrier(0)
; template <class Epi, class Sched, bool ALIGN_EPI = false, bool SP2 = false>
; __device__ __forceinline__ void gemm_phase(PG8_LAS unsigned char* lds, const Gemm g, const Sched& S, const Epi& E) {
;     ...
;             PG8_LDB(B0, 0, 0); PG8_LDB(B1, 0, 1); PG8_SCHED; PG8_LDA(At, 0, 0); PG8_STAGE(PG8_SA(1, 1), a1 + hstep, voffA);
;             PG8_WAIT_V(8); PG8_WAIT_L(0); PG8_BAR; PG8_MMA(0, 0, At, B0); PG8_MMA(0, 1, At, B1); PG8_BAR; PG8_SCHED;
;             PG8_LDA(At, 0, 1); PG8_STAGE(PG8_SB(0, 0), b2, voffB); PG8_STAGE(PG8_SB(0, 1), b2 + hstep, voffB); PG8_STAGE(PG8_SA(0, 0), a2, voffA);
;             PG8_WAIT_V(8); PG8_WAIT_L(0); PG8_BAR; PG8_MMA(1, 0, At, B0); PG8_MMA(1, 1, At, B1); PG8_BAR; PG8_SCHED;
.Lxk_0:
	ds_read_b128 v[128:131], v140
	ds_read_b128 v[132:135], v140 offset:1024
	ds_read_b128 v[136:139], v140 offset:2048
	ds_read_b128 v[140:143], v140 offset:3072
	ds_read_b128 v[144:147], v156
	ds_read_b128 v[148:151], v156 offset:1024
	ds_read_b128 v[152:155], v156 offset:2048
	ds_read_b128 v[156:159], v156 offset:3072
	v_lshl_add_u64 v[178:179], s[4:5], 0, v[206:207]
	s_add_i32 m0, s11, 0xc000
	ds_read_b128 v[160:163], v245
	ds_read_b128 v[164:167], v245 offset:1024
	ds_read_b128 v[168:171], v245 offset:2048
	ds_read_b128 v[172:175], v245 offset:3072
	ds_read_b128 v[208:211], v245 offset:4096
	ds_read_b128 v[212:215], v245 offset:5120
	ds_read_b128 v[216:219], v245 offset:6144
	ds_read_b128 v[220:223], v245 offset:7168
	global_load_lds_dwordx4 v[178:179], off
	v_lshl_add_u64 v[178:179], s[4:5], 0, v[204:205]
	s_add_i32 m0, s11, 0xe000
	s_nop 0
	global_load_lds_dwordx4 v[178:179], off
	s_waitcnt vmcnt(8)
	s_waitcnt lgkmcnt(0)
	s_barrier
	v_mfma_f32_16x16x32_bf16 v[124:127], v[128:131], v[160:163], v[124:127]
	v_mfma_f32_16x16x32_bf16 v[120:123], v[136:139], v[160:163], v[120:123]
	v_mfma_f32_16x16x32_bf16 v[108:111], v[128:131], v[168:171], v[108:111]
	v_mfma_f32_16x16x32_bf16 v[104:107], v[136:139], v[168:171], v[104:107]
	v_mfma_f32_16x16x32_bf16 v[92:95], v[128:131], v[208:211], v[92:95]
	v_mfma_f32_16x16x32_bf16 v[88:91], v[136:139], v[208:211], v[88:91]
	v_mfma_f32_16x16x32_bf16 v[76:79], v[128:131], v[216:219], v[76:79]
	v_mfma_f32_16x16x32_bf16 v[72:75], v[136:139], v[216:219], v[72:75]
	v_mfma_f32_16x16x32_bf16 v[124:127], v[132:135], v[164:167], v[124:127]
	v_mfma_f32_16x16x32_bf16 v[120:123], v[140:143], v[164:167], v[120:123]
	v_mfma_f32_16x16x32_bf16 v[108:111], v[132:135], v[172:175], v[108:111]
	v_mfma_f32_16x16x32_bf16 v[104:107], v[140:143], v[172:175], v[104:107]
	v_mfma_f32_16x16x32_bf16 v[92:95], v[132:135], v[212:215], v[92:95]
	v_mfma_f32_16x16x32_bf16 v[88:91], v[140:143], v[212:215], v[88:91]
	v_mfma_f32_16x16x32_bf16 v[76:79], v[132:135], v[220:223], v[76:79]
	v_mfma_f32_16x16x32_bf16 v[72:75], v[140:143], v[220:223], v[72:75]
	v_mfma_f32_16x16x32_bf16 v[116:119], v[144:147], v[160:163], v[116:119]
	v_mfma_f32_16x16x32_bf16 v[112:115], v[152:155], v[160:163], v[112:115]
	v_mfma_f32_16x16x32_bf16 v[100:103], v[144:147], v[168:171], v[100:103]
	v_mfma_f32_16x16x32_bf16 v[96:99], v[152:155], v[168:171], v[96:99]
	v_mfma_f32_16x16x32_bf16 v[84:87], v[144:147], v[208:211], v[84:87]
	v_mfma_f32_16x16x32_bf16 v[80:83], v[152:155], v[208:211], v[80:83]
	v_mfma_f32_16x16x32_bf16 v[68:71], v[144:147], v[216:219], v[68:71]
	v_mfma_f32_16x16x32_bf16 v[64:67], v[152:155], v[216:219], v[64:67]
	v_mfma_f32_16x16x32_bf16 v[116:119], v[148:151], v[164:167], v[116:119]
	v_mfma_f32_16x16x32_bf16 v[112:115], v[156:159], v[164:167], v[112:115]
	v_mfma_f32_16x16x32_bf16 v[100:103], v[148:151], v[172:175], v[100:103]
	v_mfma_f32_16x16x32_bf16 v[96:99], v[156:159], v[172:175], v[96:99]
	v_mfma_f32_16x16x32_bf16 v[84:87], v[148:151], v[212:215], v[84:87]
	v_mfma_f32_16x16x32_bf16 v[80:83], v[156:159], v[212:215], v[80:83]
	v_mfma_f32_16x16x32_bf16 v[68:71], v[148:151], v[220:223], v[68:71]
	v_mfma_f32_16x16x32_bf16 v[64:67], v[156:159], v[220:223], v[64:67]
	s_barrier
	s_add_i32 s63, s63, s2
	v_lshl_add_u64 v[178:179], s[56:57], 0, v[198:199]
	s_mov_b32 m0, s63
	ds_read_b128 v[160:163], v245 offset:16384
	ds_read_b128 v[164:167], v245 offset:17408
	ds_read_b128 v[168:171], v245 offset:18432
	ds_read_b128 v[172:175], v245 offset:19456
	ds_read_b128 v[208:211], v245 offset:20480
	ds_read_b128 v[212:215], v245 offset:21504
	ds_read_b128 v[216:219], v245 offset:22528
	ds_read_b128 v[220:223], v245 offset:23552
	global_load_lds_dwordx4 v[178:179], off
	s_add_i32 m0, s63, 0x2000
	s_add_u32 s64, s56, 0x40000
	v_lshl_add_u64 v[224:225], s[56:57], 0, v[194:195]
	s_addc_u32 s65, s57, 0
	s_add_i32 s63, s66, s2
	global_load_lds_dwordx4 v[224:225], off
	v_lshl_add_u64 v[226:227], s[64:65], 0, v[198:199]
	s_mov_b32 m0, s63
	v_lshl_add_u64 v[228:229], s[58:59], 0, v[196:197]
	global_load_lds_dwordx4 v[226:227], off
	v_lshl_add_u64 v[226:227], s[64:65], 0, v[194:195]
	s_add_i32 m0, s63, 0x2000
	s_nop 0
	global_load_lds_dwordx4 v[226:227], off
	v_lshl_add_u64 v[226:227], s[58:59], 0, v[200:201]
	s_mov_b32 m0, s11
	s_nop 0
	global_load_lds_dwordx4 v[226:227], off
	s_mov_b32 m0, s20
	s_nop 0
	global_load_lds_dwordx4 v[228:229], off
	s_waitcnt vmcnt(8)
	s_waitcnt lgkmcnt(0)
	s_barrier
	v_mfma_f32_16x16x32_bf16 v[60:63], v[128:131], v[160:163], v[60:63]
	v_mfma_f32_16x16x32_bf16 v[56:59], v[136:139], v[160:163], v[56:59]
	v_mfma_f32_16x16x32_bf16 v[48:51], v[128:131], v[168:171], v[48:51]
	v_mfma_f32_16x16x32_bf16 v[40:43], v[136:139], v[168:171], v[40:43]
	v_mfma_f32_16x16x32_bf16 v[32:35], v[128:131], v[208:211], v[32:35]
	v_mfma_f32_16x16x32_bf16 v[24:27], v[136:139], v[208:211], v[24:27]
	v_mfma_f32_16x16x32_bf16 v[16:19], v[128:131], v[216:219], v[16:19]
	v_mfma_f32_16x16x32_bf16 v[8:11], v[136:139], v[216:219], v[8:11]
	v_mfma_f32_16x16x32_bf16 v[60:63], v[132:135], v[164:167], v[60:63]
	v_mfma_f32_16x16x32_bf16 v[56:59], v[140:143], v[164:167], v[56:59]
	v_mfma_f32_16x16x32_bf16 v[48:51], v[132:135], v[172:175], v[48:51]
	v_mfma_f32_16x16x32_bf16 v[40:43], v[140:143], v[172:175], v[40:43]
	v_mfma_f32_16x16x32_bf16 v[32:35], v[132:135], v[212:215], v[32:35]
	v_mfma_f32_16x16x32_bf16 v[24:27], v[140:143], v[212:215], v[24:27]
	v_mfma_f32_16x16x32_bf16 v[16:19], v[132:135], v[220:223], v[16:19]
	v_mfma_f32_16x16x32_bf16 v[8:11], v[140:143], v[220:223], v[8:11]
	v_mfma_f32_16x16x32_bf16 v[52:55], v[144:147], v[160:163], v[52:55]
	v_mfma_f32_16x16x32_bf16 v[44:47], v[152:155], v[160:163], v[44:47]
	v_mfma_f32_16x16x32_bf16 v[36:39], v[144:147], v[168:171], v[36:39]
	v_mfma_f32_16x16x32_bf16 v[28:31], v[152:155], v[168:171], v[28:31]
	v_mfma_f32_16x16x32_bf16 v[20:23], v[144:147], v[208:211], v[20:23]
	v_mfma_f32_16x16x32_bf16 v[12:15], v[152:155], v[208:211], v[12:15]
	v_mfma_f32_16x16x32_bf16 v[4:7], v[144:147], v[216:219], v[4:7]
	v_mfma_f32_16x16x32_bf16 v[0:3], v[152:155], v[216:219], v[0:3]
	v_mfma_f32_16x16x32_bf16 v[52:55], v[148:151], v[164:167], v[52:55]
	v_mfma_f32_16x16x32_bf16 v[44:47], v[156:159], v[164:167], v[44:47]
	v_mfma_f32_16x16x32_bf16 v[36:39], v[148:151], v[172:175], v[36:39]
	v_mfma_f32_16x16x32_bf16 v[28:31], v[156:159], v[172:175], v[28:31]
	v_mfma_f32_16x16x32_bf16 v[20:23], v[148:151], v[212:215], v[20:23]
	v_mfma_f32_16x16x32_bf16 v[12:15], v[156:159], v[212:215], v[12:15]
	v_mfma_f32_16x16x32_bf16 v[4:7], v[148:151], v[220:223], v[4:7]
	v_mfma_f32_16x16x32_bf16 v[0:3], v[156:159], v[220:223], v[0:3]
	s_barrier
; #define PG8_STAGE(bufoff, gbase, voff) do { _Pragma("unroll") for (int _i = 0; _i < 2; ++_i) \
;         __builtin_amdgcn_global_load_lds((const unsigned*)((const char*)(gbase) + (voff)[_i]), (PG8_LAS unsigned*)(lds + (bufoff) + ldsw + _i * 8192), 16, 0, 0); } while (0)
; #define PG8_LDA(dst, b, h) do { _Pragma("unroll") for (int m = 0; m < 4; ++m) _Pragma("unroll") for (int k = 0; k < 2; ++k) dst[m][k] = *(const PG8_LAS bf16x8*)(lds + PG8_SA(b, h) + aoff + m * 2048 + k * 1024); } while (0)
; #define PG8_LDB(dst, b, h) do { _Pragma("unroll") for (int n = 0; n < 2; ++n) _Pragma("unroll") for (int k = 0; k < 2; ++k) dst[n][k] = *(const PG8_LAS bf16x8*)(lds + PG8_SB(b, h) + boff + n * 2048 + k * 1024); } while (0)
; #define PG8_MMA(ai, bj, At, Bt) do { __builtin_amdgcn_s_setprio(1); _Pragma("unroll") for (int m = 0; m < 4; ++m) _Pragma("unroll") for (int n = 0; n < 2; ++n) _Pragma("unroll") for (int k = 0; k < 2; ++k) \
;         acc[ai][bj][m][n] = __builtin_amdgcn_mfma_f32_16x16x32_bf16(Bt[n][k], At[m][k], acc[ai][bj][m][n], 0, 0, 0); __builtin_amdgcn_s_setprio(0); } while (0)
; #define PG8_WAIT_V(n) asm volatile("s_waitcnt vmcnt(" #n ")" ::: "memory")
; #define PG8_WAIT_L(n) asm volatile("s_waitcnt lgkmcnt(" #n ")" ::: "memory")
; #define PG8_BAR __builtin_amdgcn_s_barrier()
; #define PG8_SCHED __builtin_amdgcn_sched_barrier(0)
; template <class Epi, class Sched, bool ALIGN_EPI = false, bool SP2 = false>
; __device__ __forceinline__ void gemm_phase(PG8_LAS unsigned char* lds, const Gemm g, const Sched& S, const Epi& E) {
;     ...
;             PG8_LDB(B0, 1, 0); PG8_LDB(B1, 1, 1); PG8_SCHED; PG8_LDA(At, 1, 0); PG8_STAGE(PG8_SA(0, 1), a2 + hstep, voffA);
;             PG8_WAIT_V(8); PG8_WAIT_L(0); PG8_BAR; PG8_MMA(0, 0, At, B0); PG8_MMA(0, 1, At, B1); PG8_BAR; PG8_SCHED;
	s_add_i32 s63, 0, 0x18000
	s_add_i32 s64, 0, 0x1c000
	v_add_u32_e32 v140, s63, v249
	v_add_u32_e32 v156, s64, v249
	ds_read_b128 v[128:131], v140
	ds_read_b128 v[132:135], v140 offset:1024
	ds_read_b128 v[136:139], v140 offset:2048
	ds_read_b128 v[140:143], v140 offset:3072
	ds_read_b128 v[144:147], v156
	ds_read_b128 v[148:151], v156 offset:1024
	ds_read_b128 v[152:155], v156 offset:2048
	ds_read_b128 v[156:159], v156 offset:3072
	s_add_u32 s58, s58, 0x40000
	s_addc_u32 s59, s59, 0
	s_mov_b32 m0, s21
	v_lshl_add_u64 v[230:231], s[58:59], 0, v[200:201]
	ds_read_b128 v[160:163], v245 offset:32768
	ds_read_b128 v[164:167], v245 offset:33792
	ds_read_b128 v[168:171], v245 offset:34816
	ds_read_b128 v[172:175], v245 offset:35840
	ds_read_b128 v[208:211], v245 offset:36864
	ds_read_b128 v[212:215], v245 offset:37888
	ds_read_b128 v[216:219], v245 offset:38912
	ds_read_b128 v[220:223], v245 offset:39936
	global_load_lds_dwordx4 v[230:231], off
	v_lshl_add_u64 v[230:231], s[58:59], 0, v[196:197]
	s_mov_b32 m0, s22
	s_nop 0
	global_load_lds_dwordx4 v[230:231], off
	s_waitcnt vmcnt(8)
	s_waitcnt lgkmcnt(0)
	s_barrier
	v_mfma_f32_16x16x32_bf16 v[124:127], v[128:131], v[160:163], v[124:127]
	v_mfma_f32_16x16x32_bf16 v[120:123], v[136:139], v[160:163], v[120:123]
	v_mfma_f32_16x16x32_bf16 v[108:111], v[128:131], v[168:171], v[108:111]
	v_mfma_f32_16x16x32_bf16 v[104:107], v[136:139], v[168:171], v[104:107]
	v_mfma_f32_16x16x32_bf16 v[92:95], v[128:131], v[208:211], v[92:95]
	v_mfma_f32_16x16x32_bf16 v[88:91], v[136:139], v[208:211], v[88:91]
	v_mfma_f32_16x16x32_bf16 v[76:79], v[128:131], v[216:219], v[76:79]
	v_mfma_f32_16x16x32_bf16 v[72:75], v[136:139], v[216:219], v[72:75]
	v_mfma_f32_16x16x32_bf16 v[124:127], v[132:135], v[164:167], v[124:127]
	v_mfma_f32_16x16x32_bf16 v[120:123], v[140:143], v[164:167], v[120:123]
	v_mfma_f32_16x16x32_bf16 v[108:111], v[132:135], v[172:175], v[108:111]
	v_mfma_f32_16x16x32_bf16 v[104:107], v[140:143], v[172:175], v[104:107]
	v_mfma_f32_16x16x32_bf16 v[92:95], v[132:135], v[212:215], v[92:95]
	v_mfma_f32_16x16x32_bf16 v[88:91], v[140:143], v[212:215], v[88:91]
	v_mfma_f32_16x16x32_bf16 v[76:79], v[132:135], v[220:223], v[76:79]
	v_mfma_f32_16x16x32_bf16 v[72:75], v[140:143], v[220:223], v[72:75]
	v_mfma_f32_16x16x32_bf16 v[116:119], v[144:147], v[160:163], v[116:119]
	v_mfma_f32_16x16x32_bf16 v[112:115], v[152:155], v[160:163], v[112:115]
	v_mfma_f32_16x16x32_bf16 v[100:103], v[144:147], v[168:171], v[100:103]
	v_mfma_f32_16x16x32_bf16 v[96:99], v[152:155], v[168:171], v[96:99]
	v_mfma_f32_16x16x32_bf16 v[84:87], v[144:147], v[208:211], v[84:87]
	v_mfma_f32_16x16x32_bf16 v[80:83], v[152:155], v[208:211], v[80:83]
	v_mfma_f32_16x16x32_bf16 v[68:71], v[144:147], v[216:219], v[68:71]
	v_mfma_f32_16x16x32_bf16 v[64:67], v[152:155], v[216:219], v[64:67]
	v_mfma_f32_16x16x32_bf16 v[116:119], v[148:151], v[164:167], v[116:119]
	v_mfma_f32_16x16x32_bf16 v[112:115], v[156:159], v[164:167], v[112:115]
	v_mfma_f32_16x16x32_bf16 v[100:103], v[148:151], v[172:175], v[100:103]
	v_mfma_f32_16x16x32_bf16 v[96:99], v[156:159], v[172:175], v[96:99]
	v_mfma_f32_16x16x32_bf16 v[84:87], v[148:151], v[212:215], v[84:87]
	v_mfma_f32_16x16x32_bf16 v[80:83], v[156:159], v[212:215], v[80:83]
	v_mfma_f32_16x16x32_bf16 v[68:71], v[148:151], v[220:223], v[68:71]
	v_mfma_f32_16x16x32_bf16 v[64:67], v[156:159], v[220:223], v[64:67]
	s_barrier
; #define PG8_STAGE(bufoff, gbase, voff) do { _Pragma("unroll") for (int _i = 0; _i < 2; ++_i) \
;         __builtin_amdgcn_global_load_lds((const unsigned*)((const char*)(gbase) + (voff)[_i]), (PG8_LAS unsigned*)(lds + (bufoff) + ldsw + _i * 8192), 16, 0, 0); } while (0)
; #define PG8_LDA(dst, b, h) do { _Pragma("unroll") for (int m = 0; m < 4; ++m) _Pragma("unroll") for (int k = 0; k < 2; ++k) dst[m][k] = *(const PG8_LAS bf16x8*)(lds + PG8_SA(b, h) + aoff + m * 2048 + k * 1024); } while (0)
; #define PG8_MMA(ai, bj, At, Bt) do { __builtin_amdgcn_s_setprio(1); _Pragma("unroll") for (int m = 0; m < 4; ++m) _Pragma("unroll") for (int n = 0; n < 2; ++n) _Pragma("unroll") for (int k = 0; k < 2; ++k) \
;         acc[ai][bj][m][n] = __builtin_amdgcn_mfma_f32_16x16x32_bf16(Bt[n][k], At[m][k], acc[ai][bj][m][n], 0, 0, 0); __builtin_amdgcn_s_setprio(0); } while (0)
; #define PG8_WAIT_V(n) asm volatile("s_waitcnt vmcnt(" #n ")" ::: "memory")
; #define PG8_WAIT_L(n) asm volatile("s_waitcnt lgkmcnt(" #n ")" ::: "memory")
; #define PG8_BAR __builtin_amdgcn_s_barrier()
; #define PG8_SCHED __builtin_amdgcn_sched_barrier(0)
; template <class Epi, class Sched, bool ALIGN_EPI = false, bool SP2 = false>
; __device__ __forceinline__ void gemm_phase(PG8_LAS unsigned char* lds, const Gemm g, const Sched& S, const Epi& E) {
;     ...
;         for (int t = 0; t < nt; t += 2) {
;             const bool last = (t == nt - 2);
;             const char* a1 = cA + (size_t)(t + 1) * kstep;
;             const char* a2 = last ? nA : cA + (size_t)(t + 2) * kstep; const char* b2 = last ? nB : cB + (size_t)(t + 2) * kstep;
;             const char* a3 = a2 + kstep; const char* b3 = b2 + kstep;
;     ...
;             PG8_LDA(At, 1, 1); PG8_STAGE(PG8_SB(1, 0), b3, voffB); PG8_STAGE(PG8_SB(1, 1), b3 + hstep, voffB); PG8_STAGE(PG8_SA(1, 0), a3, voffA);
;             PG8_WAIT_V(8); PG8_WAIT_L(0); PG8_BAR; PG8_MMA(1, 0, At, B0); PG8_MMA(1, 1, At, B1); PG8_BAR; PG8_SCHED;
	s_add_i32 s58, s63, s2
	v_lshl_add_u64 v[178:179], v[178:179], 0, s[36:37]
	s_mov_b32 m0, s58
	ds_read_b128 v[160:163], v245 offset:49152
	ds_read_b128 v[164:167], v245 offset:50176
	ds_read_b128 v[168:171], v245 offset:51200
	ds_read_b128 v[172:175], v245 offset:52224
	ds_read_b128 v[208:211], v245 offset:53248
	ds_read_b128 v[212:215], v245 offset:54272
	ds_read_b128 v[216:219], v245 offset:55296
	ds_read_b128 v[220:223], v245 offset:56320
	global_load_lds_dwordx4 v[178:179], off
	s_add_i32 m0, s58, 0x2000
	s_add_u32 s56, s56, 0x40080
	v_lshl_add_u64 v[178:179], v[224:225], 0, s[36:37]
	s_addc_u32 s57, s57, 0
	s_add_i32 s58, s64, s2
	global_load_lds_dwordx4 v[178:179], off
	v_lshl_add_u64 v[178:179], s[56:57], 0, v[198:199]
	s_mov_b32 m0, s58
	s_nop 0
	global_load_lds_dwordx4 v[178:179], off
	v_lshl_add_u64 v[178:179], s[56:57], 0, v[194:195]
	s_add_i32 m0, s58, 0x2000
	s_nop 0
	global_load_lds_dwordx4 v[178:179], off
	v_lshl_add_u64 v[178:179], v[226:227], 0, s[36:37]
	s_mov_b32 m0, s24
	s_nop 0
	global_load_lds_dwordx4 v[178:179], off
	v_lshl_add_u64 v[178:179], v[228:229], 0, s[36:37]
	s_mov_b32 m0, s25
	s_nop 0
	global_load_lds_dwordx4 v[178:179], off
	s_waitcnt vmcnt(8)
	s_waitcnt lgkmcnt(0)
	s_barrier
	v_mfma_f32_16x16x32_bf16 v[60:63], v[128:131], v[160:163], v[60:63]
	v_mfma_f32_16x16x32_bf16 v[56:59], v[136:139], v[160:163], v[56:59]
	v_mfma_f32_16x16x32_bf16 v[48:51], v[128:131], v[168:171], v[48:51]
	v_mfma_f32_16x16x32_bf16 v[40:43], v[136:139], v[168:171], v[40:43]
	v_mfma_f32_16x16x32_bf16 v[32:35], v[128:131], v[208:211], v[32:35]
	v_mfma_f32_16x16x32_bf16 v[24:27], v[136:139], v[208:211], v[24:27]
	v_mfma_f32_16x16x32_bf16 v[16:19], v[128:131], v[216:219], v[16:19]
	v_mfma_f32_16x16x32_bf16 v[8:11], v[136:139], v[216:219], v[8:11]
	v_mfma_f32_16x16x32_bf16 v[60:63], v[132:135], v[164:167], v[60:63]
	v_mfma_f32_16x16x32_bf16 v[56:59], v[140:143], v[164:167], v[56:59]
	v_mfma_f32_16x16x32_bf16 v[48:51], v[132:135], v[172:175], v[48:51]
	v_mfma_f32_16x16x32_bf16 v[40:43], v[140:143], v[172:175], v[40:43]
	v_mfma_f32_16x16x32_bf16 v[32:35], v[132:135], v[212:215], v[32:35]
	v_mfma_f32_16x16x32_bf16 v[24:27], v[140:143], v[212:215], v[24:27]
	v_mfma_f32_16x16x32_bf16 v[16:19], v[132:135], v[220:223], v[16:19]
	v_mfma_f32_16x16x32_bf16 v[8:11], v[140:143], v[220:223], v[8:11]
	v_mfma_f32_16x16x32_bf16 v[52:55], v[144:147], v[160:163], v[52:55]
	s_add_i32 s62, s62, 2
	v_mfma_f32_16x16x32_bf16 v[44:47], v[152:155], v[160:163], v[44:47]
	s_add_u32 s49, s49, 0x100
	v_mfma_f32_16x16x32_bf16 v[36:39], v[144:147], v[168:171], v[36:39]
	s_addc_u32 s51, s51, 0
	v_mfma_f32_16x16x32_bf16 v[28:31], v[152:155], v[168:171], v[28:31]
	s_add_u32 s4, s4, 0x100
	v_mfma_f32_16x16x32_bf16 v[20:23], v[144:147], v[208:211], v[20:23]
	s_addc_u32 s5, s5, 0
	v_mfma_f32_16x16x32_bf16 v[12:15], v[152:155], v[208:211], v[12:15]
	s_add_u32 s56, s4, 0xfffc0080
	v_mfma_f32_16x16x32_bf16 v[4:7], v[144:147], v[216:219], v[4:7]
	s_addc_u32 s57, s5, -1
	v_mfma_f32_16x16x32_bf16 v[0:3], v[152:155], v[216:219], v[0:3]
	s_add_i32 s63, 0, 0x10000
	v_mfma_f32_16x16x32_bf16 v[52:55], v[148:151], v[164:167], v[52:55]
	s_cmp_eq_u32 s62, 12
	v_mfma_f32_16x16x32_bf16 v[44:47], v[156:159], v[164:167], v[44:47]
	s_cselect_b32 s59, s31, s57
	v_mfma_f32_16x16x32_bf16 v[36:39], v[148:151], v[172:175], v[36:39]
	s_cselect_b32 s58, s33, s56
	v_mfma_f32_16x16x32_bf16 v[28:31], v[156:159], v[172:175], v[28:31]
	s_cselect_b32 s57, s34, s51
	v_mfma_f32_16x16x32_bf16 v[20:23], v[148:151], v[212:215], v[20:23]
	s_cselect_b32 s56, s35, s49
	v_mfma_f32_16x16x32_bf16 v[12:15], v[156:159], v[212:215], v[12:15]
	s_add_i32 s66, 0, 0x14000
	v_mfma_f32_16x16x32_bf16 v[4:7], v[148:151], v[220:223], v[4:7]
	s_cmp_gt_u32 s62, 13
	v_mfma_f32_16x16x32_bf16 v[0:3], v[156:159], v[220:223], v[0:3]
	s_barrier
	s_nop 3
	v_add_u32_e32 v140, s63, v249
	v_add_u32_e32 v156, s66, v249
	s_cbranch_scc0 .Lxk_0
	s_and_b64 vcc, exec, s[44:45]
	s_cbranch_vccz .LBB0_146
	s_barrier

; #define PG8_STAGE(bufoff, gbase, voff) do { _Pragma("unroll") for (int _i = 0; _i < 2; ++_i) \
;         __builtin_amdgcn_global_load_lds((const unsigned*)((const char*)(gbase) + (voff)[_i]), (PG8_LAS unsigned*)(lds + (bufoff) + ldsw + _i * 8192), 16, 0, 0); } while (0)
; #define PG8_LDA(dst, b, h) do { _Pragma("unroll") for (int m = 0; m < 4; ++m) _Pragma("unroll") for (int k = 0; k < 2; ++k) dst[m][k] = *(const PG8_LAS bf16x8*)(lds + PG8_SA(b, h) + aoff + m * 2048 + k * 1024); } while (0)
; #define PG8_LDB(dst, b, h) do { _Pragma("unroll") for (int n = 0; n < 2; ++n) _Pragma("unroll") for (int k = 0; k < 2; ++k) dst[n][k] = *(const PG8_LAS bf16x8*)(lds + PG8_SB(b, h) + boff + n * 2048 + k * 1024); } while (0)
; #define PG8_MMA(ai, bj, At, Bt) do { __builtin_amdgcn_s_setprio(1); _Pragma("unroll") for (int m = 0; m < 4; ++m) _Pragma("unroll") for (int n = 0; n < 2; ++n) _Pragma("unroll") for (int k = 0; k < 2; ++k) \
;         acc[ai][bj][m][n] = __builtin_amdgcn_mfma_f32_16x16x32_bf16(Bt[n][k], At[m][k], acc[ai][bj][m][n], 0, 0, 0); __builtin_amdgcn_s_setprio(0); } while (0)
; #define PG8_WAIT_V(n) asm volatile("s_waitcnt vmcnt(" #n ")" ::: "memory")
; #define PG8_WAIT_L(n) asm volatile("s_waitcnt lgkmcnt(" #n ")" ::: "memory")
; #define PG8_BAR __builtin_amdgcn_s_barrier()
; #define PG8_SCHED __builtin_amdgcn_sched_barrier(0)
; template <class Epi, class Sched, bool ALIGN_EPI = false, bool SP2 = false>
; __device__ __forceinline__ void gemm_phase(PG8_LAS unsigned char* lds, const Gemm g, const Sched& S, const Epi& E) {
;     ...
;             PG8_LDB(B0, 0, 0); PG8_LDB(B1, 0, 1); PG8_SCHED; PG8_LDA(At, 0, 0); PG8_STAGE(PG8_SA(1, 1), a1 + hstep, voffA);
;             PG8_WAIT_V(8); PG8_WAIT_L(0); PG8_BAR; PG8_MMA(0, 0, At, B0); PG8_MMA(0, 1, At, B1); PG8_BAR; PG8_SCHED;
;             PG8_LDA(At, 0, 1); PG8_STAGE(PG8_SB(0, 0), b2, voffB); PG8_STAGE(PG8_SB(0, 1), b2 + hstep, voffB); PG8_STAGE(PG8_SA(0, 0), a2, voffA);
;             PG8_WAIT_V(8); PG8_WAIT_L(0); PG8_BAR; PG8_MMA(1, 0, At, B0); PG8_MMA(1, 1, At, B1); PG8_BAR; PG8_SCHED;
.Lxk_1:
	ds_read_b128 v[142:145], v146
	ds_read_b128 v[154:157], v146 offset:1024
	ds_read_b128 v[158:161], v146 offset:2048
	ds_read_b128 v[162:165], v146 offset:3072
	v_add_u32_e32 v146, s30, v149
	ds_read_b128 v[166:169], v146
	ds_read_b128 v[170:173], v146 offset:1024
	ds_read_b128 v[194:197], v146 offset:2048
	ds_read_b128 v[198:201], v146 offset:3072
	v_lshl_add_u64 v[146:147], s[0:1], 0, v[140:141]
	s_add_i32 m0, s54, 0xc000
	ds_read_b128 v[202:205], v153
	ds_read_b128 v[206:209], v153 offset:1024
	ds_read_b128 v[210:213], v153 offset:2048
	ds_read_b128 v[214:217], v153 offset:3072
	ds_read_b128 v[218:221], v153 offset:4096
	ds_read_b128 v[222:225], v153 offset:5120
	ds_read_b128 v[226:229], v153 offset:6144
	ds_read_b128 v[230:233], v153 offset:7168
	global_load_lds_dwordx4 v[146:147], off
	v_lshl_add_u64 v[146:147], s[0:1], 0, v[138:139]
	s_add_i32 m0, s54, 0xe000
	s_nop 0
	global_load_lds_dwordx4 v[146:147], off
	s_waitcnt vmcnt(8)
	s_waitcnt lgkmcnt(0)
	s_barrier
	v_mfma_f32_16x16x32_bf16 v[124:127], v[142:145], v[202:205], v[124:127]
	v_mfma_f32_16x16x32_bf16 v[120:123], v[158:161], v[202:205], v[120:123]
	v_mfma_f32_16x16x32_bf16 v[108:111], v[142:145], v[210:213], v[108:111]
	v_mfma_f32_16x16x32_bf16 v[104:107], v[158:161], v[210:213], v[104:107]
	v_mfma_f32_16x16x32_bf16 v[92:95], v[142:145], v[218:221], v[92:95]
	v_mfma_f32_16x16x32_bf16 v[88:91], v[158:161], v[218:221], v[88:91]
	v_mfma_f32_16x16x32_bf16 v[76:79], v[142:145], v[226:229], v[76:79]
	v_mfma_f32_16x16x32_bf16 v[72:75], v[158:161], v[226:229], v[72:75]
	v_mfma_f32_16x16x32_bf16 v[124:127], v[154:157], v[206:209], v[124:127]
	v_mfma_f32_16x16x32_bf16 v[120:123], v[162:165], v[206:209], v[120:123]
	v_mfma_f32_16x16x32_bf16 v[108:111], v[154:157], v[214:217], v[108:111]
	v_mfma_f32_16x16x32_bf16 v[104:107], v[162:165], v[214:217], v[104:107]
	v_mfma_f32_16x16x32_bf16 v[92:95], v[154:157], v[222:225], v[92:95]
	v_mfma_f32_16x16x32_bf16 v[88:91], v[162:165], v[222:225], v[88:91]
	v_mfma_f32_16x16x32_bf16 v[76:79], v[154:157], v[230:233], v[76:79]
	v_mfma_f32_16x16x32_bf16 v[72:75], v[162:165], v[230:233], v[72:75]
	v_mfma_f32_16x16x32_bf16 v[116:119], v[166:169], v[202:205], v[116:119]
	v_mfma_f32_16x16x32_bf16 v[112:115], v[194:197], v[202:205], v[112:115]
	v_mfma_f32_16x16x32_bf16 v[100:103], v[166:169], v[210:213], v[100:103]
	v_mfma_f32_16x16x32_bf16 v[96:99], v[194:197], v[210:213], v[96:99]
	v_mfma_f32_16x16x32_bf16 v[84:87], v[166:169], v[218:221], v[84:87]
	v_mfma_f32_16x16x32_bf16 v[80:83], v[194:197], v[218:221], v[80:83]
	v_mfma_f32_16x16x32_bf16 v[68:71], v[166:169], v[226:229], v[68:71]
	v_mfma_f32_16x16x32_bf16 v[64:67], v[194:197], v[226:229], v[64:67]
	v_mfma_f32_16x16x32_bf16 v[116:119], v[170:173], v[206:209], v[116:119]
	v_mfma_f32_16x16x32_bf16 v[112:115], v[198:201], v[206:209], v[112:115]
	v_mfma_f32_16x16x32_bf16 v[100:103], v[170:173], v[214:217], v[100:103]
	v_mfma_f32_16x16x32_bf16 v[96:99], v[198:201], v[214:217], v[96:99]
	v_mfma_f32_16x16x32_bf16 v[84:87], v[170:173], v[222:225], v[84:87]
	v_mfma_f32_16x16x32_bf16 v[80:83], v[198:201], v[222:225], v[80:83]
	v_mfma_f32_16x16x32_bf16 v[68:71], v[170:173], v[230:233], v[68:71]
	v_mfma_f32_16x16x32_bf16 v[64:67], v[198:201], v[230:233], v[64:67]
	s_barrier
	s_add_i32 s25, s25, s2
	v_lshl_add_u64 v[146:147], s[16:17], 0, v[132:133]
	s_mov_b32 m0, s25
	ds_read_b128 v[202:205], v153 offset:16384
	ds_read_b128 v[206:209], v153 offset:17408
	ds_read_b128 v[210:213], v153 offset:18432
	ds_read_b128 v[214:217], v153 offset:19456
	ds_read_b128 v[218:221], v153 offset:20480
	ds_read_b128 v[222:225], v153 offset:21504
	ds_read_b128 v[226:229], v153 offset:22528
	ds_read_b128 v[230:233], v153 offset:23552
	global_load_lds_dwordx4 v[146:147], off
	s_add_i32 m0, s25, 0x2000
	s_add_u32 s28, s16, 0x40000
	v_lshl_add_u64 v[174:175], s[16:17], 0, v[128:129]
	s_addc_u32 s29, s17, 0
	s_add_i32 s25, s30, s2
	global_load_lds_dwordx4 v[174:175], off
	v_lshl_add_u64 v[178:179], s[28:29], 0, v[132:133]
	s_mov_b32 m0, s25
	v_lshl_add_u64 v[234:235], s[26:27], 0, v[130:131]
	global_load_lds_dwordx4 v[178:179], off
	v_lshl_add_u64 v[178:179], s[28:29], 0, v[128:129]
	s_add_i32 m0, s25, 0x2000
	s_nop 0
	global_load_lds_dwordx4 v[178:179], off
	v_lshl_add_u64 v[178:179], s[26:27], 0, v[134:135]
	s_mov_b32 m0, s54
	s_nop 0
	global_load_lds_dwordx4 v[178:179], off
	s_mov_b32 m0, s55
	s_nop 0
	global_load_lds_dwordx4 v[234:235], off
	s_waitcnt vmcnt(8)
	s_waitcnt lgkmcnt(0)
	s_barrier
	v_mfma_f32_16x16x32_bf16 v[60:63], v[142:145], v[202:205], v[60:63]
	v_mfma_f32_16x16x32_bf16 v[56:59], v[158:161], v[202:205], v[56:59]
	v_mfma_f32_16x16x32_bf16 v[44:47], v[142:145], v[210:213], v[44:47]
	v_mfma_f32_16x16x32_bf16 v[40:43], v[158:161], v[210:213], v[40:43]
	v_mfma_f32_16x16x32_bf16 v[28:31], v[142:145], v[218:221], v[28:31]
	v_mfma_f32_16x16x32_bf16 v[24:27], v[158:161], v[218:221], v[24:27]
	v_mfma_f32_16x16x32_bf16 v[12:15], v[142:145], v[226:229], v[12:15]
	v_mfma_f32_16x16x32_bf16 v[8:11], v[158:161], v[226:229], v[8:11]
	v_mfma_f32_16x16x32_bf16 v[60:63], v[154:157], v[206:209], v[60:63]
	v_mfma_f32_16x16x32_bf16 v[56:59], v[162:165], v[206:209], v[56:59]
	v_mfma_f32_16x16x32_bf16 v[44:47], v[154:157], v[214:217], v[44:47]
	v_mfma_f32_16x16x32_bf16 v[40:43], v[162:165], v[214:217], v[40:43]
	v_mfma_f32_16x16x32_bf16 v[28:31], v[154:157], v[222:225], v[28:31]
	v_mfma_f32_16x16x32_bf16 v[24:27], v[162:165], v[222:225], v[24:27]
	v_mfma_f32_16x16x32_bf16 v[12:15], v[154:157], v[230:233], v[12:15]
	v_mfma_f32_16x16x32_bf16 v[8:11], v[162:165], v[230:233], v[8:11]
	v_mfma_f32_16x16x32_bf16 v[52:55], v[166:169], v[202:205], v[52:55]
	v_mfma_f32_16x16x32_bf16 v[48:51], v[194:197], v[202:205], v[48:51]
	v_mfma_f32_16x16x32_bf16 v[36:39], v[166:169], v[210:213], v[36:39]
	v_mfma_f32_16x16x32_bf16 v[32:35], v[194:197], v[210:213], v[32:35]
	v_mfma_f32_16x16x32_bf16 v[20:23], v[166:169], v[218:221], v[20:23]
	v_mfma_f32_16x16x32_bf16 v[16:19], v[194:197], v[218:221], v[16:19]
	v_mfma_f32_16x16x32_bf16 v[4:7], v[166:169], v[226:229], v[4:7]
	v_mfma_f32_16x16x32_bf16 v[0:3], v[194:197], v[226:229], v[0:3]
	v_mfma_f32_16x16x32_bf16 v[52:55], v[170:173], v[206:209], v[52:55]
	v_mfma_f32_16x16x32_bf16 v[48:51], v[198:201], v[206:209], v[48:51]
	v_mfma_f32_16x16x32_bf16 v[36:39], v[170:173], v[214:217], v[36:39]
	v_mfma_f32_16x16x32_bf16 v[32:35], v[198:201], v[214:217], v[32:35]
	v_mfma_f32_16x16x32_bf16 v[20:23], v[170:173], v[222:225], v[20:23]
	v_mfma_f32_16x16x32_bf16 v[16:19], v[198:201], v[222:225], v[16:19]
	v_mfma_f32_16x16x32_bf16 v[4:7], v[170:173], v[230:233], v[4:7]
	v_mfma_f32_16x16x32_bf16 v[0:3], v[198:201], v[230:233], v[0:3]
	s_barrier
; #define PG8_STAGE(bufoff, gbase, voff) do { _Pragma("unroll") for (int _i = 0; _i < 2; ++_i) \
;         __builtin_amdgcn_global_load_lds((const unsigned*)((const char*)(gbase) + (voff)[_i]), (PG8_LAS unsigned*)(lds + (bufoff) + ldsw + _i * 8192), 16, 0, 0); } while (0)
; #define PG8_LDA(dst, b, h) do { _Pragma("unroll") for (int m = 0; m < 4; ++m) _Pragma("unroll") for (int k = 0; k < 2; ++k) dst[m][k] = *(const PG8_LAS bf16x8*)(lds + PG8_SA(b, h) + aoff + m * 2048 + k * 1024); } while (0)
; #define PG8_LDB(dst, b, h) do { _Pragma("unroll") for (int n = 0; n < 2; ++n) _Pragma("unroll") for (int k = 0; k < 2; ++k) dst[n][k] = *(const PG8_LAS bf16x8*)(lds + PG8_SB(b, h) + boff + n * 2048 + k * 1024); } while (0)
; #define PG8_MMA(ai, bj, At, Bt) do { __builtin_amdgcn_s_setprio(1); _Pragma("unroll") for (int m = 0; m < 4; ++m) _Pragma("unroll") for (int n = 0; n < 2; ++n) _Pragma("unroll") for (int k = 0; k < 2; ++k) \
;         acc[ai][bj][m][n] = __builtin_amdgcn_mfma_f32_16x16x32_bf16(Bt[n][k], At[m][k], acc[ai][bj][m][n], 0, 0, 0); __builtin_amdgcn_s_setprio(0); } while (0)
; #define PG8_WAIT_V(n) asm volatile("s_waitcnt vmcnt(" #n ")" ::: "memory")
; #define PG8_WAIT_L(n) asm volatile("s_waitcnt lgkmcnt(" #n ")" ::: "memory")
; #define PG8_BAR __builtin_amdgcn_s_barrier()
; #define PG8_SCHED __builtin_amdgcn_sched_barrier(0)
; template <class Epi, class Sched, bool ALIGN_EPI = false, bool SP2 = false>
; __device__ __forceinline__ void gemm_phase(PG8_LAS unsigned char* lds, const Gemm g, const Sched& S, const Epi& E) {
;     ...
;             PG8_LDB(B0, 1, 0); PG8_LDB(B1, 1, 1); PG8_SCHED; PG8_LDA(At, 1, 0); PG8_STAGE(PG8_SA(0, 1), a2 + hstep, voffA);
;             PG8_WAIT_V(8); PG8_WAIT_L(0); PG8_BAR; PG8_MMA(0, 0, At, B0); PG8_MMA(0, 1, At, B1); PG8_BAR; PG8_SCHED;
	s_add_i32 s25, 0, 0x18000
	v_add_u32_e32 v148, s25, v149
	s_add_i32 s28, 0, 0x1c000
	ds_read_b128 v[142:145], v148
	ds_read_b128 v[154:157], v148 offset:1024
	ds_read_b128 v[158:161], v148 offset:2048
	ds_read_b128 v[162:165], v148 offset:3072
	v_add_u32_e32 v148, s28, v149
	ds_read_b128 v[166:169], v148
	ds_read_b128 v[170:173], v148 offset:1024
	ds_read_b128 v[194:197], v148 offset:2048
	ds_read_b128 v[198:201], v148 offset:3072
	s_add_u32 s26, s26, 0x40000
	s_addc_u32 s27, s27, 0
	s_mov_b32 m0, s56
	v_lshl_add_u64 v[236:237], s[26:27], 0, v[134:135]
	ds_read_b128 v[202:205], v153 offset:32768
	ds_read_b128 v[206:209], v153 offset:33792
	ds_read_b128 v[210:213], v153 offset:34816
	ds_read_b128 v[214:217], v153 offset:35840
	ds_read_b128 v[218:221], v153 offset:36864
	ds_read_b128 v[222:225], v153 offset:37888
	ds_read_b128 v[226:229], v153 offset:38912
	ds_read_b128 v[230:233], v153 offset:39936
	global_load_lds_dwordx4 v[236:237], off
	v_lshl_add_u64 v[236:237], s[26:27], 0, v[130:131]
	s_mov_b32 m0, s57
	s_nop 0
	global_load_lds_dwordx4 v[236:237], off
	s_waitcnt vmcnt(8)
	s_waitcnt lgkmcnt(0)
	s_barrier
	v_mfma_f32_16x16x32_bf16 v[124:127], v[142:145], v[202:205], v[124:127]
	v_mfma_f32_16x16x32_bf16 v[120:123], v[158:161], v[202:205], v[120:123]
	v_mfma_f32_16x16x32_bf16 v[108:111], v[142:145], v[210:213], v[108:111]
	v_mfma_f32_16x16x32_bf16 v[104:107], v[158:161], v[210:213], v[104:107]
	v_mfma_f32_16x16x32_bf16 v[92:95], v[142:145], v[218:221], v[92:95]
	v_mfma_f32_16x16x32_bf16 v[88:91], v[158:161], v[218:221], v[88:91]
	v_mfma_f32_16x16x32_bf16 v[76:79], v[142:145], v[226:229], v[76:79]
	v_mfma_f32_16x16x32_bf16 v[72:75], v[158:161], v[226:229], v[72:75]
	v_mfma_f32_16x16x32_bf16 v[124:127], v[154:157], v[206:209], v[124:127]
	v_mfma_f32_16x16x32_bf16 v[120:123], v[162:165], v[206:209], v[120:123]
	v_mfma_f32_16x16x32_bf16 v[108:111], v[154:157], v[214:217], v[108:111]
	v_mfma_f32_16x16x32_bf16 v[104:107], v[162:165], v[214:217], v[104:107]
	v_mfma_f32_16x16x32_bf16 v[92:95], v[154:157], v[222:225], v[92:95]
	v_mfma_f32_16x16x32_bf16 v[88:91], v[162:165], v[222:225], v[88:91]
	v_mfma_f32_16x16x32_bf16 v[76:79], v[154:157], v[230:233], v[76:79]
	v_mfma_f32_16x16x32_bf16 v[72:75], v[162:165], v[230:233], v[72:75]
	v_mfma_f32_16x16x32_bf16 v[116:119], v[166:169], v[202:205], v[116:119]
	v_mfma_f32_16x16x32_bf16 v[112:115], v[194:197], v[202:205], v[112:115]
	v_mfma_f32_16x16x32_bf16 v[100:103], v[166:169], v[210:213], v[100:103]
	v_mfma_f32_16x16x32_bf16 v[96:99], v[194:197], v[210:213], v[96:99]
	v_mfma_f32_16x16x32_bf16 v[84:87], v[166:169], v[218:221], v[84:87]
	v_mfma_f32_16x16x32_bf16 v[80:83], v[194:197], v[218:221], v[80:83]
	v_mfma_f32_16x16x32_bf16 v[68:71], v[166:169], v[226:229], v[68:71]
	v_mfma_f32_16x16x32_bf16 v[64:67], v[194:197], v[226:229], v[64:67]
	v_mfma_f32_16x16x32_bf16 v[116:119], v[170:173], v[206:209], v[116:119]
	v_mfma_f32_16x16x32_bf16 v[112:115], v[198:201], v[206:209], v[112:115]
	v_mfma_f32_16x16x32_bf16 v[100:103], v[170:173], v[214:217], v[100:103]
	v_mfma_f32_16x16x32_bf16 v[96:99], v[198:201], v[214:217], v[96:99]
	v_mfma_f32_16x16x32_bf16 v[84:87], v[170:173], v[222:225], v[84:87]
	v_mfma_f32_16x16x32_bf16 v[80:83], v[198:201], v[222:225], v[80:83]
	v_mfma_f32_16x16x32_bf16 v[68:71], v[170:173], v[230:233], v[68:71]
	v_mfma_f32_16x16x32_bf16 v[64:67], v[198:201], v[230:233], v[64:67]
	s_barrier
; #define PG8_STAGE(bufoff, gbase, voff) do { _Pragma("unroll") for (int _i = 0; _i < 2; ++_i) \
;         __builtin_amdgcn_global_load_lds((const unsigned*)((const char*)(gbase) + (voff)[_i]), (PG8_LAS unsigned*)(lds + (bufoff) + ldsw + _i * 8192), 16, 0, 0); } while (0)
; #define PG8_LDA(dst, b, h) do { _Pragma("unroll") for (int m = 0; m < 4; ++m) _Pragma("unroll") for (int k = 0; k < 2; ++k) dst[m][k] = *(const PG8_LAS bf16x8*)(lds + PG8_SA(b, h) + aoff + m * 2048 + k * 1024); } while (0)
; #define PG8_MMA(ai, bj, At, Bt) do { __builtin_amdgcn_s_setprio(1); _Pragma("unroll") for (int m = 0; m < 4; ++m) _Pragma("unroll") for (int n = 0; n < 2; ++n) _Pragma("unroll") for (int k = 0; k < 2; ++k) \
;         acc[ai][bj][m][n] = __builtin_amdgcn_mfma_f32_16x16x32_bf16(Bt[n][k], At[m][k], acc[ai][bj][m][n], 0, 0, 0); __builtin_amdgcn_s_setprio(0); } while (0)
; #define PG8_WAIT_V(n) asm volatile("s_waitcnt vmcnt(" #n ")" ::: "memory")
; #define PG8_WAIT_L(n) asm volatile("s_waitcnt lgkmcnt(" #n ")" ::: "memory")
; #define PG8_BAR __builtin_amdgcn_s_barrier()
; #define PG8_SCHED __builtin_amdgcn_sched_barrier(0)
; template <class Epi, class Sched, bool ALIGN_EPI = false, bool SP2 = false>
; __device__ __forceinline__ void gemm_phase(PG8_LAS unsigned char* lds, const Gemm g, const Sched& S, const Epi& E) {
;     ...
;         for (int t = 0; t < nt; t += 2) {
;             const bool last = (t == nt - 2);
;             const char* a1 = cA + (size_t)(t + 1) * kstep;
;             const char* a2 = last ? nA : cA + (size_t)(t + 2) * kstep; const char* b2 = last ? nB : cB + (size_t)(t + 2) * kstep;
;             const char* a3 = a2 + kstep; const char* b3 = b2 + kstep;
;     ...
;             PG8_LDA(At, 1, 1); PG8_STAGE(PG8_SB(1, 0), b3, voffB); PG8_STAGE(PG8_SB(1, 1), b3 + hstep, voffB); PG8_STAGE(PG8_SA(1, 0), a3, voffA);
;             PG8_WAIT_V(8); PG8_WAIT_L(0); PG8_BAR; PG8_MMA(1, 0, At, B0); PG8_MMA(1, 1, At, B1); PG8_BAR; PG8_SCHED;
	s_add_i32 s25, s25, s2
	v_lshl_add_u64 v[146:147], v[146:147], 0, s[36:37]
	s_mov_b32 m0, s25
	ds_read_b128 v[202:205], v153 offset:49152
	ds_read_b128 v[206:209], v153 offset:50176
	ds_read_b128 v[210:213], v153 offset:51200
	ds_read_b128 v[214:217], v153 offset:52224
	ds_read_b128 v[218:221], v153 offset:53248
	ds_read_b128 v[222:225], v153 offset:54272
	ds_read_b128 v[226:229], v153 offset:55296
	ds_read_b128 v[230:233], v153 offset:56320
	global_load_lds_dwordx4 v[146:147], off
	s_add_i32 m0, s25, 0x2000
	s_add_u32 s16, s16, 0x40080
	v_lshl_add_u64 v[146:147], v[174:175], 0, s[36:37]
	s_addc_u32 s17, s17, 0
	s_add_i32 s25, s28, s2
	global_load_lds_dwordx4 v[146:147], off
	v_lshl_add_u64 v[146:147], s[16:17], 0, v[132:133]
	s_mov_b32 m0, s25
	s_nop 0
	global_load_lds_dwordx4 v[146:147], off
	v_lshl_add_u64 v[146:147], s[16:17], 0, v[128:129]
	s_add_i32 m0, s25, 0x2000
	s_nop 0
	global_load_lds_dwordx4 v[146:147], off
	v_lshl_add_u64 v[146:147], v[178:179], 0, s[36:37]
	s_mov_b32 m0, s59
	s_nop 0
	global_load_lds_dwordx4 v[146:147], off
	v_lshl_add_u64 v[146:147], v[234:235], 0, s[36:37]
	s_mov_b32 m0, s62
	s_nop 0
	global_load_lds_dwordx4 v[146:147], off
	s_waitcnt vmcnt(8)
	s_waitcnt lgkmcnt(0)
	s_barrier
	v_mfma_f32_16x16x32_bf16 v[60:63], v[142:145], v[202:205], v[60:63]
	v_mfma_f32_16x16x32_bf16 v[56:59], v[158:161], v[202:205], v[56:59]
	v_mfma_f32_16x16x32_bf16 v[44:47], v[142:145], v[210:213], v[44:47]
	v_mfma_f32_16x16x32_bf16 v[40:43], v[158:161], v[210:213], v[40:43]
	v_mfma_f32_16x16x32_bf16 v[28:31], v[142:145], v[218:221], v[28:31]
	v_mfma_f32_16x16x32_bf16 v[24:27], v[158:161], v[218:221], v[24:27]
	v_mfma_f32_16x16x32_bf16 v[12:15], v[142:145], v[226:229], v[12:15]
	v_mfma_f32_16x16x32_bf16 v[8:11], v[158:161], v[226:229], v[8:11]
	v_mfma_f32_16x16x32_bf16 v[60:63], v[154:157], v[206:209], v[60:63]
	v_mfma_f32_16x16x32_bf16 v[56:59], v[162:165], v[206:209], v[56:59]
	v_mfma_f32_16x16x32_bf16 v[44:47], v[154:157], v[214:217], v[44:47]
	v_mfma_f32_16x16x32_bf16 v[40:43], v[162:165], v[214:217], v[40:43]
	v_mfma_f32_16x16x32_bf16 v[28:31], v[154:157], v[222:225], v[28:31]
	v_mfma_f32_16x16x32_bf16 v[24:27], v[162:165], v[222:225], v[24:27]
	v_mfma_f32_16x16x32_bf16 v[12:15], v[154:157], v[230:233], v[12:15]
	v_mfma_f32_16x16x32_bf16 v[8:11], v[162:165], v[230:233], v[8:11]
	v_mfma_f32_16x16x32_bf16 v[52:55], v[166:169], v[202:205], v[52:55]
	s_add_i32 s24, s24, 2
	v_mfma_f32_16x16x32_bf16 v[48:51], v[194:197], v[202:205], v[48:51]
	s_add_u32 s22, s22, 0x100
	v_mfma_f32_16x16x32_bf16 v[36:39], v[166:169], v[210:213], v[36:39]
	s_addc_u32 s23, s23, 0
	v_mfma_f32_16x16x32_bf16 v[32:35], v[194:197], v[210:213], v[32:35]
	s_add_u32 s0, s0, 0x100
	v_mfma_f32_16x16x32_bf16 v[20:23], v[166:169], v[218:221], v[20:23]
	s_addc_u32 s1, s1, 0
	v_mfma_f32_16x16x32_bf16 v[16:19], v[194:197], v[218:221], v[16:19]
	s_add_u32 s16, s0, 0xfffc0080
	v_mfma_f32_16x16x32_bf16 v[4:7], v[166:169], v[226:229], v[4:7]
	s_addc_u32 s17, s1, -1
	v_mfma_f32_16x16x32_bf16 v[0:3], v[194:197], v[226:229], v[0:3]
	s_add_i32 s25, 0, 0x10000
	v_mfma_f32_16x16x32_bf16 v[52:55], v[170:173], v[206:209], v[52:55]
	s_cmp_eq_u32 s24, 12
	v_mfma_f32_16x16x32_bf16 v[48:51], v[198:201], v[206:209], v[48:51]
	s_cselect_b32 s27, s11, s17
	v_mfma_f32_16x16x32_bf16 v[36:39], v[170:173], v[214:217], v[36:39]
	s_cselect_b32 s26, s14, s16
	v_mfma_f32_16x16x32_bf16 v[32:35], v[198:201], v[214:217], v[32:35]
	s_cselect_b32 s17, s20, s23
	v_mfma_f32_16x16x32_bf16 v[20:23], v[170:173], v[222:225], v[20:23]
	s_cselect_b32 s16, s21, s22
	v_mfma_f32_16x16x32_bf16 v[16:19], v[198:201], v[222:225], v[16:19]
	s_add_i32 s30, 0, 0x14000
	v_mfma_f32_16x16x32_bf16 v[4:7], v[170:173], v[230:233], v[4:7]
	s_cmp_gt_u32 s24, 13
	v_mfma_f32_16x16x32_bf16 v[0:3], v[198:201], v[230:233], v[0:3]
	s_barrier
	s_nop 3
	v_add_u32_e32 v146, s25, v149
	s_cbranch_scc0 .Lxk_1
	s_and_b64 vcc, exec, s[44:45]
	s_cbranch_vccz .LBB0_268
	s_barrier

; #define PG8_STAGE(bufoff, gbase, voff) do { _Pragma("unroll") for (int _i = 0; _i < 2; ++_i) \
;         __builtin_amdgcn_global_load_lds((const unsigned*)((const char*)(gbase) + (voff)[_i]), (PG8_LAS unsigned*)(lds + (bufoff) + ldsw + _i * 8192), 16, 0, 0); } while (0)
; #define PG8_LDA(dst, b, h) do { _Pragma("unroll") for (int m = 0; m < 4; ++m) _Pragma("unroll") for (int k = 0; k < 2; ++k) dst[m][k] = *(const PG8_LAS bf16x8*)(lds + PG8_SA(b, h) + aoff + m * 2048 + k * 1024); } while (0)
; #define PG8_LDB(dst, b, h) do { _Pragma("unroll") for (int n = 0; n < 2; ++n) _Pragma("unroll") for (int k = 0; k < 2; ++k) dst[n][k] = *(const PG8_LAS bf16x8*)(lds + PG8_SB(b, h) + boff + n * 2048 + k * 1024); } while (0)
; #define PG8_MMA(ai, bj, At, Bt) do { __builtin_amdgcn_s_setprio(1); _Pragma("unroll") for (int m = 0; m < 4; ++m) _Pragma("unroll") for (int n = 0; n < 2; ++n) _Pragma("unroll") for (int k = 0; k < 2; ++k) \
;         acc[ai][bj][m][n] = __builtin_amdgcn_mfma_f32_16x16x32_bf16(Bt[n][k], At[m][k], acc[ai][bj][m][n], 0, 0, 0); __builtin_amdgcn_s_setprio(0); } while (0)
; #define PG8_WAIT_V(n) asm volatile("s_waitcnt vmcnt(" #n ")" ::: "memory")
; #define PG8_WAIT_L(n) asm volatile("s_waitcnt lgkmcnt(" #n ")" ::: "memory")
; #define PG8_BAR __builtin_amdgcn_s_barrier()
; #define PG8_SCHED __builtin_amdgcn_sched_barrier(0)
; template <class Epi, class Sched, bool ALIGN_EPI = false, bool SP2 = false>
; __device__ __forceinline__ void gemm_phase(PG8_LAS unsigned char* lds, const Gemm g, const Sched& S, const Epi& E) {
;     ...
;             PG8_LDB(B0, 0, 0); PG8_LDB(B1, 0, 1); PG8_SCHED; PG8_LDA(At, 0, 0); PG8_STAGE(PG8_SA(1, 1), a1 + hstep, voffA);
;             PG8_WAIT_V(8); PG8_WAIT_L(0); PG8_BAR; PG8_MMA(0, 0, At, B0); PG8_MMA(0, 1, At, B1); PG8_BAR; PG8_SCHED;
;             PG8_LDA(At, 0, 1); PG8_STAGE(PG8_SB(0, 0), b2, voffB); PG8_STAGE(PG8_SB(0, 1), b2 + hstep, voffB); PG8_STAGE(PG8_SA(0, 0), a2, voffA);
;             PG8_WAIT_V(8); PG8_WAIT_L(0); PG8_BAR; PG8_MMA(1, 0, At, B0); PG8_MMA(1, 1, At, B1); PG8_BAR; PG8_SCHED;
.Lxk_2:
	ds_read_b128 v[112:115], v124
	ds_read_b128 v[116:119], v124 offset:1024
	ds_read_b128 v[120:123], v124 offset:2048
	ds_read_b128 v[124:127], v124 offset:3072
	ds_read_b128 v[128:131], v168
	ds_read_b128 v[132:135], v168 offset:1024
	ds_read_b128 v[164:167], v168 offset:2048
	ds_read_b128 v[168:171], v168 offset:3072
	v_lshl_add_u64 v[178:179], s[48:49], 0, v[162:163]
	s_add_i32 m0, s21, 0xc000
	ds_read_b128 v[172:175], v203
	ds_read_b128 v[194:197], v203 offset:1024
	ds_read_b128 v[204:207], v203 offset:2048
	ds_read_b128 v[208:211], v203 offset:3072
	ds_read_b128 v[212:215], v203 offset:4096
	ds_read_b128 v[216:219], v203 offset:5120
	ds_read_b128 v[220:223], v203 offset:6144
	ds_read_b128 v[224:227], v203 offset:7168
	global_load_lds_dwordx4 v[178:179], off
	v_lshl_add_u64 v[178:179], s[48:49], 0, v[160:161]
	s_add_i32 m0, s21, 0xe000
	s_nop 0
	global_load_lds_dwordx4 v[178:179], off
	s_waitcnt vmcnt(8)
	s_waitcnt lgkmcnt(0)
	s_barrier
	v_mfma_f32_16x16x32_bf16 v[148:151], v[112:115], v[172:175], v[148:151]
	v_mfma_f32_16x16x32_bf16 v[144:147], v[120:123], v[172:175], v[144:147]
	v_mfma_f32_16x16x32_bf16 v[108:111], v[112:115], v[204:207], v[108:111]
	v_mfma_f32_16x16x32_bf16 v[104:107], v[120:123], v[204:207], v[104:107]
	v_mfma_f32_16x16x32_bf16 v[92:95], v[112:115], v[212:215], v[92:95]
	v_mfma_f32_16x16x32_bf16 v[88:91], v[120:123], v[212:215], v[88:91]
	v_mfma_f32_16x16x32_bf16 v[76:79], v[112:115], v[220:223], v[76:79]
	v_mfma_f32_16x16x32_bf16 v[72:75], v[120:123], v[220:223], v[72:75]
	v_mfma_f32_16x16x32_bf16 v[148:151], v[116:119], v[194:197], v[148:151]
	v_mfma_f32_16x16x32_bf16 v[144:147], v[124:127], v[194:197], v[144:147]
	v_mfma_f32_16x16x32_bf16 v[108:111], v[116:119], v[208:211], v[108:111]
	v_mfma_f32_16x16x32_bf16 v[104:107], v[124:127], v[208:211], v[104:107]
	v_mfma_f32_16x16x32_bf16 v[92:95], v[116:119], v[216:219], v[92:95]
	v_mfma_f32_16x16x32_bf16 v[88:91], v[124:127], v[216:219], v[88:91]
	v_mfma_f32_16x16x32_bf16 v[76:79], v[116:119], v[224:227], v[76:79]
	v_mfma_f32_16x16x32_bf16 v[72:75], v[124:127], v[224:227], v[72:75]
	v_mfma_f32_16x16x32_bf16 v[140:143], v[128:131], v[172:175], v[140:143]
	v_mfma_f32_16x16x32_bf16 v[136:139], v[164:167], v[172:175], v[136:139]
	v_mfma_f32_16x16x32_bf16 v[100:103], v[128:131], v[204:207], v[100:103]
	v_mfma_f32_16x16x32_bf16 v[96:99], v[164:167], v[204:207], v[96:99]
	v_mfma_f32_16x16x32_bf16 v[84:87], v[128:131], v[212:215], v[84:87]
	v_mfma_f32_16x16x32_bf16 v[80:83], v[164:167], v[212:215], v[80:83]
	v_mfma_f32_16x16x32_bf16 v[68:71], v[128:131], v[220:223], v[68:71]
	v_mfma_f32_16x16x32_bf16 v[64:67], v[164:167], v[220:223], v[64:67]
	v_mfma_f32_16x16x32_bf16 v[140:143], v[132:135], v[194:197], v[140:143]
	v_mfma_f32_16x16x32_bf16 v[136:139], v[168:171], v[194:197], v[136:139]
	v_mfma_f32_16x16x32_bf16 v[100:103], v[132:135], v[208:211], v[100:103]
	v_mfma_f32_16x16x32_bf16 v[96:99], v[168:171], v[208:211], v[96:99]
	v_mfma_f32_16x16x32_bf16 v[84:87], v[132:135], v[216:219], v[84:87]
	v_mfma_f32_16x16x32_bf16 v[80:83], v[168:171], v[216:219], v[80:83]
	v_mfma_f32_16x16x32_bf16 v[68:71], v[132:135], v[224:227], v[68:71]
	v_mfma_f32_16x16x32_bf16 v[64:67], v[168:171], v[224:227], v[64:67]
	s_barrier
	s_add_i32 s56, s56, s20
	v_lshl_add_u64 v[178:179], s[50:51], 0, v[156:157]
	s_mov_b32 m0, s56
	ds_read_b128 v[172:175], v203 offset:16384
	ds_read_b128 v[194:197], v203 offset:17408
	ds_read_b128 v[204:207], v203 offset:18432
	ds_read_b128 v[208:211], v203 offset:19456
	ds_read_b128 v[212:215], v203 offset:20480
	ds_read_b128 v[216:219], v203 offset:21504
	ds_read_b128 v[220:223], v203 offset:22528
	ds_read_b128 v[224:227], v203 offset:23552
	global_load_lds_dwordx4 v[178:179], off
	s_add_i32 m0, s56, 0x2000
	s_add_u32 s56, s50, 0x40000
	v_lshl_add_u64 v[198:199], s[50:51], 0, v[152:153]
	s_addc_u32 s57, s51, 0
	s_add_i32 s58, s58, s20
	global_load_lds_dwordx4 v[198:199], off
	v_lshl_add_u64 v[228:229], s[56:57], 0, v[156:157]
	s_mov_b32 m0, s58
	v_lshl_add_u64 v[230:231], s[52:53], 0, v[154:155]
	global_load_lds_dwordx4 v[228:229], off
	v_lshl_add_u64 v[228:229], s[56:57], 0, v[152:153]
	s_add_i32 m0, s58, 0x2000
	s_nop 0
	global_load_lds_dwordx4 v[228:229], off
	v_lshl_add_u64 v[228:229], s[52:53], 0, v[158:159]
	s_mov_b32 m0, s21
	s_nop 0
	global_load_lds_dwordx4 v[228:229], off
	s_mov_b32 m0, s22
	s_nop 0
	global_load_lds_dwordx4 v[230:231], off
	s_waitcnt vmcnt(8)
	s_waitcnt lgkmcnt(0)
	s_barrier
	v_mfma_f32_16x16x32_bf16 v[60:63], v[112:115], v[172:175], v[60:63]
	v_mfma_f32_16x16x32_bf16 v[56:59], v[120:123], v[172:175], v[56:59]
	v_mfma_f32_16x16x32_bf16 v[44:47], v[112:115], v[204:207], v[44:47]
	v_mfma_f32_16x16x32_bf16 v[40:43], v[120:123], v[204:207], v[40:43]
	v_mfma_f32_16x16x32_bf16 v[28:31], v[112:115], v[212:215], v[28:31]
	v_mfma_f32_16x16x32_bf16 v[24:27], v[120:123], v[212:215], v[24:27]
	v_mfma_f32_16x16x32_bf16 v[12:15], v[112:115], v[220:223], v[12:15]
	v_mfma_f32_16x16x32_bf16 v[8:11], v[120:123], v[220:223], v[8:11]
	v_mfma_f32_16x16x32_bf16 v[60:63], v[116:119], v[194:197], v[60:63]
	v_mfma_f32_16x16x32_bf16 v[56:59], v[124:127], v[194:197], v[56:59]
	v_mfma_f32_16x16x32_bf16 v[44:47], v[116:119], v[208:211], v[44:47]
	v_mfma_f32_16x16x32_bf16 v[40:43], v[124:127], v[208:211], v[40:43]
	v_mfma_f32_16x16x32_bf16 v[28:31], v[116:119], v[216:219], v[28:31]
	v_mfma_f32_16x16x32_bf16 v[24:27], v[124:127], v[216:219], v[24:27]
	v_mfma_f32_16x16x32_bf16 v[12:15], v[116:119], v[224:227], v[12:15]
	v_mfma_f32_16x16x32_bf16 v[8:11], v[124:127], v[224:227], v[8:11]
	v_mfma_f32_16x16x32_bf16 v[52:55], v[128:131], v[172:175], v[52:55]
	v_mfma_f32_16x16x32_bf16 v[48:51], v[164:167], v[172:175], v[48:51]
	v_mfma_f32_16x16x32_bf16 v[36:39], v[128:131], v[204:207], v[36:39]
	v_mfma_f32_16x16x32_bf16 v[32:35], v[164:167], v[204:207], v[32:35]
	v_mfma_f32_16x16x32_bf16 v[20:23], v[128:131], v[212:215], v[20:23]
	v_mfma_f32_16x16x32_bf16 v[16:19], v[164:167], v[212:215], v[16:19]
	v_mfma_f32_16x16x32_bf16 v[4:7], v[128:131], v[220:223], v[4:7]
	v_mfma_f32_16x16x32_bf16 v[0:3], v[164:167], v[220:223], v[0:3]
	v_mfma_f32_16x16x32_bf16 v[52:55], v[132:135], v[194:197], v[52:55]
	v_mfma_f32_16x16x32_bf16 v[48:51], v[168:171], v[194:197], v[48:51]
	v_mfma_f32_16x16x32_bf16 v[36:39], v[132:135], v[208:211], v[36:39]
	v_mfma_f32_16x16x32_bf16 v[32:35], v[168:171], v[208:211], v[32:35]
	v_mfma_f32_16x16x32_bf16 v[20:23], v[132:135], v[216:219], v[20:23]
	v_mfma_f32_16x16x32_bf16 v[16:19], v[168:171], v[216:219], v[16:19]
	v_mfma_f32_16x16x32_bf16 v[4:7], v[132:135], v[224:227], v[4:7]
	v_mfma_f32_16x16x32_bf16 v[0:3], v[168:171], v[224:227], v[0:3]
	s_barrier
; #define PG8_STAGE(bufoff, gbase, voff) do { _Pragma("unroll") for (int _i = 0; _i < 2; ++_i) \
;         __builtin_amdgcn_global_load_lds((const unsigned*)((const char*)(gbase) + (voff)[_i]), (PG8_LAS unsigned*)(lds + (bufoff) + ldsw + _i * 8192), 16, 0, 0); } while (0)
; #define PG8_LDA(dst, b, h) do { _Pragma("unroll") for (int m = 0; m < 4; ++m) _Pragma("unroll") for (int k = 0; k < 2; ++k) dst[m][k] = *(const PG8_LAS bf16x8*)(lds + PG8_SA(b, h) + aoff + m * 2048 + k * 1024); } while (0)
; #define PG8_LDB(dst, b, h) do { _Pragma("unroll") for (int n = 0; n < 2; ++n) _Pragma("unroll") for (int k = 0; k < 2; ++k) dst[n][k] = *(const PG8_LAS bf16x8*)(lds + PG8_SB(b, h) + boff + n * 2048 + k * 1024); } while (0)
; #define PG8_MMA(ai, bj, At, Bt) do { __builtin_amdgcn_s_setprio(1); _Pragma("unroll") for (int m = 0; m < 4; ++m) _Pragma("unroll") for (int n = 0; n < 2; ++n) _Pragma("unroll") for (int k = 0; k < 2; ++k) \
;         acc[ai][bj][m][n] = __builtin_amdgcn_mfma_f32_16x16x32_bf16(Bt[n][k], At[m][k], acc[ai][bj][m][n], 0, 0, 0); __builtin_amdgcn_s_setprio(0); } while (0)
; #define PG8_WAIT_V(n) asm volatile("s_waitcnt vmcnt(" #n ")" ::: "memory")
; #define PG8_WAIT_L(n) asm volatile("s_waitcnt lgkmcnt(" #n ")" ::: "memory")
; #define PG8_BAR __builtin_amdgcn_s_barrier()
; #define PG8_SCHED __builtin_amdgcn_sched_barrier(0)
; template <class Epi, class Sched, bool ALIGN_EPI = false, bool SP2 = false>
; __device__ __forceinline__ void gemm_phase(PG8_LAS unsigned char* lds, const Gemm g, const Sched& S, const Epi& E) {
;     ...
;             PG8_LDB(B0, 1, 0); PG8_LDB(B1, 1, 1); PG8_SCHED; PG8_LDA(At, 1, 0); PG8_STAGE(PG8_SA(0, 1), a2 + hstep, voffA);
;             PG8_WAIT_V(8); PG8_WAIT_L(0); PG8_BAR; PG8_MMA(0, 0, At, B0); PG8_MMA(0, 1, At, B1); PG8_BAR; PG8_SCHED;
	s_add_i32 s56, 0, 0x18000
	s_add_i32 s57, 0, 0x1c000
	v_add_u32_e32 v124, s56, v201
	v_add_u32_e32 v168, s57, v201
	ds_read_b128 v[112:115], v124
	ds_read_b128 v[116:119], v124 offset:1024
	ds_read_b128 v[120:123], v124 offset:2048
	ds_read_b128 v[124:127], v124 offset:3072
	ds_read_b128 v[128:131], v168
	ds_read_b128 v[132:135], v168 offset:1024
	ds_read_b128 v[164:167], v168 offset:2048
	ds_read_b128 v[168:171], v168 offset:3072
	s_add_u32 s52, s52, 0x40000
	s_addc_u32 s53, s53, 0
	s_mov_b32 m0, s23
	v_lshl_add_u64 v[232:233], s[52:53], 0, v[158:159]
	ds_read_b128 v[172:175], v203 offset:32768
	ds_read_b128 v[194:197], v203 offset:33792
	ds_read_b128 v[204:207], v203 offset:34816
	ds_read_b128 v[208:211], v203 offset:35840
	ds_read_b128 v[212:215], v203 offset:36864
	ds_read_b128 v[216:219], v203 offset:37888
	ds_read_b128 v[220:223], v203 offset:38912
	ds_read_b128 v[224:227], v203 offset:39936
	global_load_lds_dwordx4 v[232:233], off
	v_lshl_add_u64 v[232:233], s[52:53], 0, v[154:155]
	s_mov_b32 m0, s24
	s_nop 0
	global_load_lds_dwordx4 v[232:233], off
	s_waitcnt vmcnt(8)
	s_waitcnt lgkmcnt(0)
	s_barrier
	v_mfma_f32_16x16x32_bf16 v[148:151], v[112:115], v[172:175], v[148:151]
	v_mfma_f32_16x16x32_bf16 v[144:147], v[120:123], v[172:175], v[144:147]
	v_mfma_f32_16x16x32_bf16 v[108:111], v[112:115], v[204:207], v[108:111]
	v_mfma_f32_16x16x32_bf16 v[104:107], v[120:123], v[204:207], v[104:107]
	v_mfma_f32_16x16x32_bf16 v[92:95], v[112:115], v[212:215], v[92:95]
	v_mfma_f32_16x16x32_bf16 v[88:91], v[120:123], v[212:215], v[88:91]
	v_mfma_f32_16x16x32_bf16 v[76:79], v[112:115], v[220:223], v[76:79]
	v_mfma_f32_16x16x32_bf16 v[72:75], v[120:123], v[220:223], v[72:75]
	v_mfma_f32_16x16x32_bf16 v[148:151], v[116:119], v[194:197], v[148:151]
	v_mfma_f32_16x16x32_bf16 v[144:147], v[124:127], v[194:197], v[144:147]
	v_mfma_f32_16x16x32_bf16 v[108:111], v[116:119], v[208:211], v[108:111]
	v_mfma_f32_16x16x32_bf16 v[104:107], v[124:127], v[208:211], v[104:107]
	v_mfma_f32_16x16x32_bf16 v[92:95], v[116:119], v[216:219], v[92:95]
	v_mfma_f32_16x16x32_bf16 v[88:91], v[124:127], v[216:219], v[88:91]
	v_mfma_f32_16x16x32_bf16 v[76:79], v[116:119], v[224:227], v[76:79]
	v_mfma_f32_16x16x32_bf16 v[72:75], v[124:127], v[224:227], v[72:75]
	v_mfma_f32_16x16x32_bf16 v[140:143], v[128:131], v[172:175], v[140:143]
	v_mfma_f32_16x16x32_bf16 v[136:139], v[164:167], v[172:175], v[136:139]
	v_mfma_f32_16x16x32_bf16 v[100:103], v[128:131], v[204:207], v[100:103]
	v_mfma_f32_16x16x32_bf16 v[96:99], v[164:167], v[204:207], v[96:99]
	v_mfma_f32_16x16x32_bf16 v[84:87], v[128:131], v[212:215], v[84:87]
	v_mfma_f32_16x16x32_bf16 v[80:83], v[164:167], v[212:215], v[80:83]
	v_mfma_f32_16x16x32_bf16 v[68:71], v[128:131], v[220:223], v[68:71]
	v_mfma_f32_16x16x32_bf16 v[64:67], v[164:167], v[220:223], v[64:67]
	v_mfma_f32_16x16x32_bf16 v[140:143], v[132:135], v[194:197], v[140:143]
	v_mfma_f32_16x16x32_bf16 v[136:139], v[168:171], v[194:197], v[136:139]
	v_mfma_f32_16x16x32_bf16 v[100:103], v[132:135], v[208:211], v[100:103]
	v_mfma_f32_16x16x32_bf16 v[96:99], v[168:171], v[208:211], v[96:99]
	v_mfma_f32_16x16x32_bf16 v[84:87], v[132:135], v[216:219], v[84:87]
	v_mfma_f32_16x16x32_bf16 v[80:83], v[168:171], v[216:219], v[80:83]
	v_mfma_f32_16x16x32_bf16 v[68:71], v[132:135], v[224:227], v[68:71]
	v_mfma_f32_16x16x32_bf16 v[64:67], v[168:171], v[224:227], v[64:67]
	s_barrier
; #define PG8_STAGE(bufoff, gbase, voff) do { _Pragma("unroll") for (int _i = 0; _i < 2; ++_i) \
;         __builtin_amdgcn_global_load_lds((const unsigned*)((const char*)(gbase) + (voff)[_i]), (PG8_LAS unsigned*)(lds + (bufoff) + ldsw + _i * 8192), 16, 0, 0); } while (0)
; #define PG8_LDA(dst, b, h) do { _Pragma("unroll") for (int m = 0; m < 4; ++m) _Pragma("unroll") for (int k = 0; k < 2; ++k) dst[m][k] = *(const PG8_LAS bf16x8*)(lds + PG8_SA(b, h) + aoff + m * 2048 + k * 1024); } while (0)
; #define PG8_MMA(ai, bj, At, Bt) do { __builtin_amdgcn_s_setprio(1); _Pragma("unroll") for (int m = 0; m < 4; ++m) _Pragma("unroll") for (int n = 0; n < 2; ++n) _Pragma("unroll") for (int k = 0; k < 2; ++k) \
;         acc[ai][bj][m][n] = __builtin_amdgcn_mfma_f32_16x16x32_bf16(Bt[n][k], At[m][k], acc[ai][bj][m][n], 0, 0, 0); __builtin_amdgcn_s_setprio(0); } while (0)
; #define PG8_WAIT_V(n) asm volatile("s_waitcnt vmcnt(" #n ")" ::: "memory")
; #define PG8_WAIT_L(n) asm volatile("s_waitcnt lgkmcnt(" #n ")" ::: "memory")
; #define PG8_BAR __builtin_amdgcn_s_barrier()
; #define PG8_SCHED __builtin_amdgcn_sched_barrier(0)
; template <class Epi, class Sched, bool ALIGN_EPI = false, bool SP2 = false>
; __device__ __forceinline__ void gemm_phase(PG8_LAS unsigned char* lds, const Gemm g, const Sched& S, const Epi& E) {
;     ...
;         for (int t = 0; t < nt; t += 2) {
;             const bool last = (t == nt - 2);
;             const char* a1 = cA + (size_t)(t + 1) * kstep;
;             const char* a2 = last ? nA : cA + (size_t)(t + 2) * kstep; const char* b2 = last ? nB : cB + (size_t)(t + 2) * kstep;
;             const char* a3 = a2 + kstep; const char* b3 = b2 + kstep;
;     ...
;             PG8_LDA(At, 1, 1); PG8_STAGE(PG8_SB(1, 0), b3, voffB); PG8_STAGE(PG8_SB(1, 1), b3 + hstep, voffB); PG8_STAGE(PG8_SA(1, 0), a3, voffA);
;             PG8_WAIT_V(8); PG8_WAIT_L(0); PG8_BAR; PG8_MMA(1, 0, At, B0); PG8_MMA(1, 1, At, B1); PG8_BAR; PG8_SCHED;
	s_add_i32 s52, s56, s20
	v_lshl_add_u64 v[178:179], v[178:179], 0, s[36:37]
	s_mov_b32 m0, s52
	ds_read_b128 v[172:175], v203 offset:49152
	ds_read_b128 v[194:197], v203 offset:50176
	ds_read_b128 v[204:207], v203 offset:51200
	ds_read_b128 v[208:211], v203 offset:52224
	ds_read_b128 v[212:215], v203 offset:53248
	ds_read_b128 v[216:219], v203 offset:54272
	ds_read_b128 v[220:223], v203 offset:55296
	ds_read_b128 v[224:227], v203 offset:56320
	global_load_lds_dwordx4 v[178:179], off
	s_add_i32 m0, s52, 0x2000
	s_add_u32 s50, s50, 0x40080
	v_lshl_add_u64 v[178:179], v[198:199], 0, s[36:37]
	s_addc_u32 s51, s51, 0
	s_add_i32 s52, s57, s20
	global_load_lds_dwordx4 v[178:179], off
	v_lshl_add_u64 v[178:179], s[50:51], 0, v[156:157]
	s_mov_b32 m0, s52
	s_nop 0
	global_load_lds_dwordx4 v[178:179], off
	v_lshl_add_u64 v[178:179], s[50:51], 0, v[152:153]
	s_add_i32 m0, s52, 0x2000
	s_nop 0
	global_load_lds_dwordx4 v[178:179], off
	v_lshl_add_u64 v[178:179], v[228:229], 0, s[36:37]
	s_mov_b32 m0, s28
	s_nop 0
	global_load_lds_dwordx4 v[178:179], off
	v_lshl_add_u64 v[178:179], v[230:231], 0, s[36:37]
	s_mov_b32 m0, s29
	s_nop 0
	global_load_lds_dwordx4 v[178:179], off
	s_waitcnt vmcnt(8)
	s_waitcnt lgkmcnt(0)
	s_barrier
	v_mfma_f32_16x16x32_bf16 v[60:63], v[112:115], v[172:175], v[60:63]
	v_mfma_f32_16x16x32_bf16 v[56:59], v[120:123], v[172:175], v[56:59]
	v_mfma_f32_16x16x32_bf16 v[44:47], v[112:115], v[204:207], v[44:47]
	v_mfma_f32_16x16x32_bf16 v[40:43], v[120:123], v[204:207], v[40:43]
	v_mfma_f32_16x16x32_bf16 v[28:31], v[112:115], v[212:215], v[28:31]
	v_mfma_f32_16x16x32_bf16 v[24:27], v[120:123], v[212:215], v[24:27]
	v_mfma_f32_16x16x32_bf16 v[12:15], v[112:115], v[220:223], v[12:15]
	v_mfma_f32_16x16x32_bf16 v[8:11], v[120:123], v[220:223], v[8:11]
	v_mfma_f32_16x16x32_bf16 v[60:63], v[116:119], v[194:197], v[60:63]
	v_mfma_f32_16x16x32_bf16 v[56:59], v[124:127], v[194:197], v[56:59]
	v_mfma_f32_16x16x32_bf16 v[44:47], v[116:119], v[208:211], v[44:47]
	v_mfma_f32_16x16x32_bf16 v[40:43], v[124:127], v[208:211], v[40:43]
	v_mfma_f32_16x16x32_bf16 v[28:31], v[116:119], v[216:219], v[28:31]
	v_mfma_f32_16x16x32_bf16 v[24:27], v[124:127], v[216:219], v[24:27]
	v_mfma_f32_16x16x32_bf16 v[12:15], v[116:119], v[224:227], v[12:15]
	v_mfma_f32_16x16x32_bf16 v[8:11], v[124:127], v[224:227], v[8:11]
	v_mfma_f32_16x16x32_bf16 v[52:55], v[128:131], v[172:175], v[52:55]
	s_add_i32 s55, s55, 2
	v_mfma_f32_16x16x32_bf16 v[48:51], v[164:167], v[172:175], v[48:51]
	s_add_u32 s43, s43, 0x100
	v_mfma_f32_16x16x32_bf16 v[36:39], v[128:131], v[204:207], v[36:39]
	s_addc_u32 s54, s54, 0
	v_mfma_f32_16x16x32_bf16 v[32:35], v[164:167], v[204:207], v[32:35]
	s_add_u32 s48, s48, 0x100
	v_mfma_f32_16x16x32_bf16 v[20:23], v[128:131], v[212:215], v[20:23]
	s_addc_u32 s49, s49, 0
	v_mfma_f32_16x16x32_bf16 v[16:19], v[164:167], v[212:215], v[16:19]
	s_add_u32 s50, s48, 0xfffc0080
	v_mfma_f32_16x16x32_bf16 v[4:7], v[128:131], v[220:223], v[4:7]
	s_addc_u32 s51, s49, -1
	v_mfma_f32_16x16x32_bf16 v[0:3], v[164:167], v[220:223], v[0:3]
	s_add_i32 s56, 0, 0x10000
	v_mfma_f32_16x16x32_bf16 v[52:55], v[132:135], v[194:197], v[52:55]
	s_cmp_eq_u32 s55, 12
	v_mfma_f32_16x16x32_bf16 v[48:51], v[168:171], v[194:197], v[48:51]
	s_cselect_b32 s53, s33, s51
	v_mfma_f32_16x16x32_bf16 v[36:39], v[132:135], v[208:211], v[36:39]
	s_cselect_b32 s52, s34, s50
	v_mfma_f32_16x16x32_bf16 v[32:35], v[168:171], v[208:211], v[32:35]
	s_cselect_b32 s51, s35, s54
	v_mfma_f32_16x16x32_bf16 v[20:23], v[132:135], v[216:219], v[20:23]
	s_cselect_b32 s50, s41, s43
	v_mfma_f32_16x16x32_bf16 v[16:19], v[168:171], v[216:219], v[16:19]
	s_add_i32 s58, 0, 0x14000
	v_mfma_f32_16x16x32_bf16 v[4:7], v[132:135], v[224:227], v[4:7]
	s_cmp_gt_u32 s55, 13
	v_mfma_f32_16x16x32_bf16 v[0:3], v[168:171], v[224:227], v[0:3]
	s_barrier
	s_nop 3
	v_add_u32_e32 v124, s56, v201
	v_add_u32_e32 v168, s58, v201
	s_cbranch_scc0 .Lxk_2
	s_and_b64 vcc, exec, s[26:27]
	s_cbranch_vccz .LBB0_561
	s_barrier

; #define PG8_STAGE(bufoff, gbase, voff) do { _Pragma("unroll") for (int _i = 0; _i < 2; ++_i) \
;         __builtin_amdgcn_global_load_lds((const unsigned*)((const char*)(gbase) + (voff)[_i]), (PG8_LAS unsigned*)(lds + (bufoff) + ldsw + _i * 8192), 16, 0, 0); } while (0)
; #define PG8_LDA(dst, b, h) do { _Pragma("unroll") for (int m = 0; m < 4; ++m) _Pragma("unroll") for (int k = 0; k < 2; ++k) dst[m][k] = *(const PG8_LAS bf16x8*)(lds + PG8_SA(b, h) + aoff + m * 2048 + k * 1024); } while (0)
; #define PG8_LDB(dst, b, h) do { _Pragma("unroll") for (int n = 0; n < 2; ++n) _Pragma("unroll") for (int k = 0; k < 2; ++k) dst[n][k] = *(const PG8_LAS bf16x8*)(lds + PG8_SB(b, h) + boff + n * 2048 + k * 1024); } while (0)
; #define PG8_MMA(ai, bj, At, Bt) do { __builtin_amdgcn_s_setprio(1); _Pragma("unroll") for (int m = 0; m < 4; ++m) _Pragma("unroll") for (int n = 0; n < 2; ++n) _Pragma("unroll") for (int k = 0; k < 2; ++k) \
;         acc[ai][bj][m][n] = __builtin_amdgcn_mfma_f32_16x16x32_bf16(Bt[n][k], At[m][k], acc[ai][bj][m][n], 0, 0, 0); __builtin_amdgcn_s_setprio(0); } while (0)
; #define PG8_WAIT_V(n) asm volatile("s_waitcnt vmcnt(" #n ")" ::: "memory")
; #define PG8_WAIT_L(n) asm volatile("s_waitcnt lgkmcnt(" #n ")" ::: "memory")
; #define PG8_BAR __builtin_amdgcn_s_barrier()
; #define PG8_SCHED __builtin_amdgcn_sched_barrier(0)
; template <class Epi, class Sched, bool ALIGN_EPI = false, bool SP2 = false>
; __device__ __forceinline__ void gemm_phase(PG8_LAS unsigned char* lds, const Gemm g, const Sched& S, const Epi& E) {
;     ...
;             PG8_LDB(B0, 0, 0); PG8_LDB(B1, 0, 1); PG8_SCHED; PG8_LDA(At, 0, 0); PG8_STAGE(PG8_SA(1, 1), a1 + hstep, voffA);
;             PG8_WAIT_V(8); PG8_WAIT_L(0); PG8_BAR; PG8_MMA(0, 0, At, B0); PG8_MMA(0, 1, At, B1); PG8_BAR; PG8_SCHED;
;             PG8_LDA(At, 0, 1); PG8_STAGE(PG8_SB(0, 0), b2, voffB); PG8_STAGE(PG8_SB(0, 1), b2 + hstep, voffB); PG8_STAGE(PG8_SA(0, 0), a2, voffA);
;             PG8_WAIT_V(8); PG8_WAIT_L(0); PG8_BAR; PG8_MMA(1, 0, At, B0); PG8_MMA(1, 1, At, B1); PG8_BAR; PG8_SCHED;
.Lxk_3:
	ds_read_b128 v[142:145], v141
	ds_read_b128 v[152:155], v141 offset:1024
	ds_read_b128 v[156:159], v141 offset:2048
	ds_read_b128 v[160:163], v141 offset:3072
	v_add_u32_e32 v141, s56, v148
	ds_read_b128 v[164:167], v141
	ds_read_b128 v[168:171], v141 offset:1024
	ds_read_b128 v[172:175], v141 offset:2048
	ds_read_b128 v[194:197], v141 offset:3072
	v_lshl_add_u64 v[178:179], s[46:47], 0, v[138:139]
	s_add_i32 m0, s21, 0xc000
	ds_read_b128 v[198:201], v151
	ds_read_b128 v[202:205], v151 offset:1024
	ds_read_b128 v[206:209], v151 offset:2048
	ds_read_b128 v[210:213], v151 offset:3072
	ds_read_b128 v[214:217], v151 offset:4096
	ds_read_b128 v[218:221], v151 offset:5120
	ds_read_b128 v[222:225], v151 offset:6144
	ds_read_b128 v[226:229], v151 offset:7168
	global_load_lds_dwordx4 v[178:179], off
	v_lshl_add_u64 v[178:179], s[46:47], 0, v[136:137]
	s_add_i32 m0, s21, 0xe000
	s_nop 0
	global_load_lds_dwordx4 v[178:179], off
	s_waitcnt vmcnt(8)
	s_waitcnt lgkmcnt(0)
	s_barrier
	v_mfma_f32_16x16x32_bf16 v[124:127], v[142:145], v[198:201], v[124:127]
	v_mfma_f32_16x16x32_bf16 v[120:123], v[156:159], v[198:201], v[120:123]
	v_mfma_f32_16x16x32_bf16 v[108:111], v[142:145], v[206:209], v[108:111]
	v_mfma_f32_16x16x32_bf16 v[104:107], v[156:159], v[206:209], v[104:107]
	v_mfma_f32_16x16x32_bf16 v[92:95], v[142:145], v[214:217], v[92:95]
	v_mfma_f32_16x16x32_bf16 v[88:91], v[156:159], v[214:217], v[88:91]
	v_mfma_f32_16x16x32_bf16 v[76:79], v[142:145], v[222:225], v[76:79]
	v_mfma_f32_16x16x32_bf16 v[72:75], v[156:159], v[222:225], v[72:75]
	v_mfma_f32_16x16x32_bf16 v[124:127], v[152:155], v[202:205], v[124:127]
	v_mfma_f32_16x16x32_bf16 v[120:123], v[160:163], v[202:205], v[120:123]
	v_mfma_f32_16x16x32_bf16 v[108:111], v[152:155], v[210:213], v[108:111]
	v_mfma_f32_16x16x32_bf16 v[104:107], v[160:163], v[210:213], v[104:107]
	v_mfma_f32_16x16x32_bf16 v[92:95], v[152:155], v[218:221], v[92:95]
	v_mfma_f32_16x16x32_bf16 v[88:91], v[160:163], v[218:221], v[88:91]
	v_mfma_f32_16x16x32_bf16 v[76:79], v[152:155], v[226:229], v[76:79]
	v_mfma_f32_16x16x32_bf16 v[72:75], v[160:163], v[226:229], v[72:75]
	v_mfma_f32_16x16x32_bf16 v[116:119], v[164:167], v[198:201], v[116:119]
	v_mfma_f32_16x16x32_bf16 v[112:115], v[172:175], v[198:201], v[112:115]
	v_mfma_f32_16x16x32_bf16 v[100:103], v[164:167], v[206:209], v[100:103]
	v_mfma_f32_16x16x32_bf16 v[96:99], v[172:175], v[206:209], v[96:99]
	v_mfma_f32_16x16x32_bf16 v[84:87], v[164:167], v[214:217], v[84:87]
	v_mfma_f32_16x16x32_bf16 v[80:83], v[172:175], v[214:217], v[80:83]
	v_mfma_f32_16x16x32_bf16 v[68:71], v[164:167], v[222:225], v[68:71]
	v_mfma_f32_16x16x32_bf16 v[64:67], v[172:175], v[222:225], v[64:67]
	v_mfma_f32_16x16x32_bf16 v[116:119], v[168:171], v[202:205], v[116:119]
	v_mfma_f32_16x16x32_bf16 v[112:115], v[194:197], v[202:205], v[112:115]
	v_mfma_f32_16x16x32_bf16 v[100:103], v[168:171], v[210:213], v[100:103]
	v_mfma_f32_16x16x32_bf16 v[96:99], v[194:197], v[210:213], v[96:99]
	v_mfma_f32_16x16x32_bf16 v[84:87], v[168:171], v[218:221], v[84:87]
	v_mfma_f32_16x16x32_bf16 v[80:83], v[194:197], v[218:221], v[80:83]
	v_mfma_f32_16x16x32_bf16 v[68:71], v[168:171], v[226:229], v[68:71]
	v_mfma_f32_16x16x32_bf16 v[64:67], v[194:197], v[226:229], v[64:67]
	s_barrier
	s_add_i32 s54, s54, s20
	v_lshl_add_u64 v[178:179], s[48:49], 0, v[132:133]
	s_mov_b32 m0, s54
	ds_read_b128 v[198:201], v151 offset:16384
	ds_read_b128 v[202:205], v151 offset:17408
	ds_read_b128 v[206:209], v151 offset:18432
	ds_read_b128 v[210:213], v151 offset:19456
	ds_read_b128 v[214:217], v151 offset:20480
	ds_read_b128 v[218:221], v151 offset:21504
	ds_read_b128 v[222:225], v151 offset:22528
	ds_read_b128 v[226:229], v151 offset:23552
	global_load_lds_dwordx4 v[178:179], off
	s_add_i32 m0, s54, 0x2000
	s_add_u32 s54, s48, 0x40000
	v_lshl_add_u64 v[230:231], s[48:49], 0, v[128:129]
	s_addc_u32 s55, s49, 0
	s_add_i32 s56, s56, s20
	global_load_lds_dwordx4 v[230:231], off
	v_lshl_add_u64 v[232:233], s[54:55], 0, v[132:133]
	s_mov_b32 m0, s56
	v_lshl_add_u64 v[234:235], s[50:51], 0, v[130:131]
	global_load_lds_dwordx4 v[232:233], off
	v_lshl_add_u64 v[232:233], s[54:55], 0, v[128:129]
	s_add_i32 m0, s56, 0x2000
	s_nop 0
	global_load_lds_dwordx4 v[232:233], off
	v_lshl_add_u64 v[232:233], s[50:51], 0, v[134:135]
	s_mov_b32 m0, s21
	s_nop 0
	global_load_lds_dwordx4 v[232:233], off
	s_mov_b32 m0, s22
	s_nop 0
	global_load_lds_dwordx4 v[234:235], off
	s_waitcnt vmcnt(8)
	s_waitcnt lgkmcnt(0)
	s_barrier
	v_mfma_f32_16x16x32_bf16 v[60:63], v[142:145], v[198:201], v[60:63]
	v_mfma_f32_16x16x32_bf16 v[56:59], v[156:159], v[198:201], v[56:59]
	v_mfma_f32_16x16x32_bf16 v[44:47], v[142:145], v[206:209], v[44:47]
	v_mfma_f32_16x16x32_bf16 v[40:43], v[156:159], v[206:209], v[40:43]
	v_mfma_f32_16x16x32_bf16 v[28:31], v[142:145], v[214:217], v[28:31]
	v_mfma_f32_16x16x32_bf16 v[24:27], v[156:159], v[214:217], v[24:27]
	v_mfma_f32_16x16x32_bf16 v[12:15], v[142:145], v[222:225], v[12:15]
	v_mfma_f32_16x16x32_bf16 v[8:11], v[156:159], v[222:225], v[8:11]
	v_mfma_f32_16x16x32_bf16 v[60:63], v[152:155], v[202:205], v[60:63]
	v_mfma_f32_16x16x32_bf16 v[56:59], v[160:163], v[202:205], v[56:59]
	v_mfma_f32_16x16x32_bf16 v[44:47], v[152:155], v[210:213], v[44:47]
	v_mfma_f32_16x16x32_bf16 v[40:43], v[160:163], v[210:213], v[40:43]
	v_mfma_f32_16x16x32_bf16 v[28:31], v[152:155], v[218:221], v[28:31]
	v_mfma_f32_16x16x32_bf16 v[24:27], v[160:163], v[218:221], v[24:27]
	v_mfma_f32_16x16x32_bf16 v[12:15], v[152:155], v[226:229], v[12:15]
	v_mfma_f32_16x16x32_bf16 v[8:11], v[160:163], v[226:229], v[8:11]
	v_mfma_f32_16x16x32_bf16 v[52:55], v[164:167], v[198:201], v[52:55]
	v_mfma_f32_16x16x32_bf16 v[48:51], v[172:175], v[198:201], v[48:51]
	v_mfma_f32_16x16x32_bf16 v[36:39], v[164:167], v[206:209], v[36:39]
	v_mfma_f32_16x16x32_bf16 v[32:35], v[172:175], v[206:209], v[32:35]
	v_mfma_f32_16x16x32_bf16 v[20:23], v[164:167], v[214:217], v[20:23]
	v_mfma_f32_16x16x32_bf16 v[16:19], v[172:175], v[214:217], v[16:19]
	v_mfma_f32_16x16x32_bf16 v[4:7], v[164:167], v[222:225], v[4:7]
	v_mfma_f32_16x16x32_bf16 v[0:3], v[172:175], v[222:225], v[0:3]
	v_mfma_f32_16x16x32_bf16 v[52:55], v[168:171], v[202:205], v[52:55]
	v_mfma_f32_16x16x32_bf16 v[48:51], v[194:197], v[202:205], v[48:51]
	v_mfma_f32_16x16x32_bf16 v[36:39], v[168:171], v[210:213], v[36:39]
	v_mfma_f32_16x16x32_bf16 v[32:35], v[194:197], v[210:213], v[32:35]
	v_mfma_f32_16x16x32_bf16 v[20:23], v[168:171], v[218:221], v[20:23]
	v_mfma_f32_16x16x32_bf16 v[16:19], v[194:197], v[218:221], v[16:19]
	v_mfma_f32_16x16x32_bf16 v[4:7], v[168:171], v[226:229], v[4:7]
	v_mfma_f32_16x16x32_bf16 v[0:3], v[194:197], v[226:229], v[0:3]
	s_barrier
; #define PG8_STAGE(bufoff, gbase, voff) do { _Pragma("unroll") for (int _i = 0; _i < 2; ++_i) \
;         __builtin_amdgcn_global_load_lds((const unsigned*)((const char*)(gbase) + (voff)[_i]), (PG8_LAS unsigned*)(lds + (bufoff) + ldsw + _i * 8192), 16, 0, 0); } while (0)
; #define PG8_LDA(dst, b, h) do { _Pragma("unroll") for (int m = 0; m < 4; ++m) _Pragma("unroll") for (int k = 0; k < 2; ++k) dst[m][k] = *(const PG8_LAS bf16x8*)(lds + PG8_SA(b, h) + aoff + m * 2048 + k * 1024); } while (0)
; #define PG8_LDB(dst, b, h) do { _Pragma("unroll") for (int n = 0; n < 2; ++n) _Pragma("unroll") for (int k = 0; k < 2; ++k) dst[n][k] = *(const PG8_LAS bf16x8*)(lds + PG8_SB(b, h) + boff + n * 2048 + k * 1024); } while (0)
; #define PG8_MMA(ai, bj, At, Bt) do { __builtin_amdgcn_s_setprio(1); _Pragma("unroll") for (int m = 0; m < 4; ++m) _Pragma("unroll") for (int n = 0; n < 2; ++n) _Pragma("unroll") for (int k = 0; k < 2; ++k) \
;         acc[ai][bj][m][n] = __builtin_amdgcn_mfma_f32_16x16x32_bf16(Bt[n][k], At[m][k], acc[ai][bj][m][n], 0, 0, 0); __builtin_amdgcn_s_setprio(0); } while (0)
; #define PG8_WAIT_V(n) asm volatile("s_waitcnt vmcnt(" #n ")" ::: "memory")
; #define PG8_WAIT_L(n) asm volatile("s_waitcnt lgkmcnt(" #n ")" ::: "memory")
; #define PG8_BAR __builtin_amdgcn_s_barrier()
; #define PG8_SCHED __builtin_amdgcn_sched_barrier(0)
; template <class Epi, class Sched, bool ALIGN_EPI = false, bool SP2 = false>
; __device__ __forceinline__ void gemm_phase(PG8_LAS unsigned char* lds, const Gemm g, const Sched& S, const Epi& E) {
;     ...
;             PG8_LDB(B0, 1, 0); PG8_LDB(B1, 1, 1); PG8_SCHED; PG8_LDA(At, 1, 0); PG8_STAGE(PG8_SA(0, 1), a2 + hstep, voffA);
;             PG8_WAIT_V(8); PG8_WAIT_L(0); PG8_BAR; PG8_MMA(0, 0, At, B0); PG8_MMA(0, 1, At, B1); PG8_BAR; PG8_SCHED;
	s_add_i32 s54, 0, 0x18000
	v_add_u32_e32 v141, s54, v148
	s_add_i32 s55, 0, 0x1c000
	ds_read_b128 v[142:145], v141
	ds_read_b128 v[152:155], v141 offset:1024
	ds_read_b128 v[156:159], v141 offset:2048
	ds_read_b128 v[160:163], v141 offset:3072
	v_add_u32_e32 v141, s55, v148
	ds_read_b128 v[164:167], v141
	ds_read_b128 v[168:171], v141 offset:1024
	ds_read_b128 v[172:175], v141 offset:2048
	ds_read_b128 v[194:197], v141 offset:3072
	s_add_u32 s50, s50, 0x40000
	s_addc_u32 s51, s51, 0
	s_mov_b32 m0, s23
	v_lshl_add_u64 v[236:237], s[50:51], 0, v[134:135]
	ds_read_b128 v[198:201], v151 offset:32768
	ds_read_b128 v[202:205], v151 offset:33792
	ds_read_b128 v[206:209], v151 offset:34816
	ds_read_b128 v[210:213], v151 offset:35840
	ds_read_b128 v[214:217], v151 offset:36864
	ds_read_b128 v[218:221], v151 offset:37888
	ds_read_b128 v[222:225], v151 offset:38912
	ds_read_b128 v[226:229], v151 offset:39936
	global_load_lds_dwordx4 v[236:237], off
	v_lshl_add_u64 v[236:237], s[50:51], 0, v[130:131]
	s_mov_b32 m0, s24
	s_nop 0
	global_load_lds_dwordx4 v[236:237], off
	s_waitcnt vmcnt(8)
	s_waitcnt lgkmcnt(0)
	s_barrier
	v_mfma_f32_16x16x32_bf16 v[124:127], v[142:145], v[198:201], v[124:127]
	v_mfma_f32_16x16x32_bf16 v[120:123], v[156:159], v[198:201], v[120:123]
	v_mfma_f32_16x16x32_bf16 v[108:111], v[142:145], v[206:209], v[108:111]
	v_mfma_f32_16x16x32_bf16 v[104:107], v[156:159], v[206:209], v[104:107]
	v_mfma_f32_16x16x32_bf16 v[92:95], v[142:145], v[214:217], v[92:95]
	v_mfma_f32_16x16x32_bf16 v[88:91], v[156:159], v[214:217], v[88:91]
	v_mfma_f32_16x16x32_bf16 v[76:79], v[142:145], v[222:225], v[76:79]
	v_mfma_f32_16x16x32_bf16 v[72:75], v[156:159], v[222:225], v[72:75]
	v_mfma_f32_16x16x32_bf16 v[124:127], v[152:155], v[202:205], v[124:127]
	v_mfma_f32_16x16x32_bf16 v[120:123], v[160:163], v[202:205], v[120:123]
	v_mfma_f32_16x16x32_bf16 v[108:111], v[152:155], v[210:213], v[108:111]
	v_mfma_f32_16x16x32_bf16 v[104:107], v[160:163], v[210:213], v[104:107]
	v_mfma_f32_16x16x32_bf16 v[92:95], v[152:155], v[218:221], v[92:95]
	v_mfma_f32_16x16x32_bf16 v[88:91], v[160:163], v[218:221], v[88:91]
	v_mfma_f32_16x16x32_bf16 v[76:79], v[152:155], v[226:229], v[76:79]
	v_mfma_f32_16x16x32_bf16 v[72:75], v[160:163], v[226:229], v[72:75]
	v_mfma_f32_16x16x32_bf16 v[116:119], v[164:167], v[198:201], v[116:119]
	v_mfma_f32_16x16x32_bf16 v[112:115], v[172:175], v[198:201], v[112:115]
	v_mfma_f32_16x16x32_bf16 v[100:103], v[164:167], v[206:209], v[100:103]
	v_mfma_f32_16x16x32_bf16 v[96:99], v[172:175], v[206:209], v[96:99]
	v_mfma_f32_16x16x32_bf16 v[84:87], v[164:167], v[214:217], v[84:87]
	v_mfma_f32_16x16x32_bf16 v[80:83], v[172:175], v[214:217], v[80:83]
	v_mfma_f32_16x16x32_bf16 v[68:71], v[164:167], v[222:225], v[68:71]
	v_mfma_f32_16x16x32_bf16 v[64:67], v[172:175], v[222:225], v[64:67]
	v_mfma_f32_16x16x32_bf16 v[116:119], v[168:171], v[202:205], v[116:119]
	v_mfma_f32_16x16x32_bf16 v[112:115], v[194:197], v[202:205], v[112:115]
	v_mfma_f32_16x16x32_bf16 v[100:103], v[168:171], v[210:213], v[100:103]
	v_mfma_f32_16x16x32_bf16 v[96:99], v[194:197], v[210:213], v[96:99]
	v_mfma_f32_16x16x32_bf16 v[84:87], v[168:171], v[218:221], v[84:87]
	v_mfma_f32_16x16x32_bf16 v[80:83], v[194:197], v[218:221], v[80:83]
	v_mfma_f32_16x16x32_bf16 v[68:71], v[168:171], v[226:229], v[68:71]
	v_mfma_f32_16x16x32_bf16 v[64:67], v[194:197], v[226:229], v[64:67]
	s_barrier
; #define PG8_STAGE(bufoff, gbase, voff) do { _Pragma("unroll") for (int _i = 0; _i < 2; ++_i) \
;         __builtin_amdgcn_global_load_lds((const unsigned*)((const char*)(gbase) + (voff)[_i]), (PG8_LAS unsigned*)(lds + (bufoff) + ldsw + _i * 8192), 16, 0, 0); } while (0)
; #define PG8_LDA(dst, b, h) do { _Pragma("unroll") for (int m = 0; m < 4; ++m) _Pragma("unroll") for (int k = 0; k < 2; ++k) dst[m][k] = *(const PG8_LAS bf16x8*)(lds + PG8_SA(b, h) + aoff + m * 2048 + k * 1024); } while (0)
; #define PG8_MMA(ai, bj, At, Bt) do { __builtin_amdgcn_s_setprio(1); _Pragma("unroll") for (int m = 0; m < 4; ++m) _Pragma("unroll") for (int n = 0; n < 2; ++n) _Pragma("unroll") for (int k = 0; k < 2; ++k) \
;         acc[ai][bj][m][n] = __builtin_amdgcn_mfma_f32_16x16x32_bf16(Bt[n][k], At[m][k], acc[ai][bj][m][n], 0, 0, 0); __builtin_amdgcn_s_setprio(0); } while (0)
; #define PG8_WAIT_V(n) asm volatile("s_waitcnt vmcnt(" #n ")" ::: "memory")
; #define PG8_WAIT_L(n) asm volatile("s_waitcnt lgkmcnt(" #n ")" ::: "memory")
; #define PG8_BAR __builtin_amdgcn_s_barrier()
; #define PG8_SCHED __builtin_amdgcn_sched_barrier(0)
; template <class Epi, class Sched, bool ALIGN_EPI = false, bool SP2 = false>
; __device__ __forceinline__ void gemm_phase(PG8_LAS unsigned char* lds, const Gemm g, const Sched& S, const Epi& E) {
;     ...
;         for (int t = 0; t < nt; t += 2) {
;             const bool last = (t == nt - 2);
;             const char* a1 = cA + (size_t)(t + 1) * kstep;
;             const char* a2 = last ? nA : cA + (size_t)(t + 2) * kstep; const char* b2 = last ? nB : cB + (size_t)(t + 2) * kstep;
;             const char* a3 = a2 + kstep; const char* b3 = b2 + kstep;
;     ...
;             PG8_LDA(At, 1, 1); PG8_STAGE(PG8_SB(1, 0), b3, voffB); PG8_STAGE(PG8_SB(1, 1), b3 + hstep, voffB); PG8_STAGE(PG8_SA(1, 0), a3, voffA);
;             PG8_WAIT_V(8); PG8_WAIT_L(0); PG8_BAR; PG8_MMA(1, 0, At, B0); PG8_MMA(1, 1, At, B1); PG8_BAR; PG8_SCHED;
	s_add_i32 s50, s54, s20
	v_lshl_add_u64 v[178:179], v[178:179], 0, s[36:37]
	s_mov_b32 m0, s50
	ds_read_b128 v[198:201], v151 offset:49152
	ds_read_b128 v[202:205], v151 offset:50176
	ds_read_b128 v[206:209], v151 offset:51200
	ds_read_b128 v[210:213], v151 offset:52224
	ds_read_b128 v[214:217], v151 offset:53248
	ds_read_b128 v[218:221], v151 offset:54272
	ds_read_b128 v[222:225], v151 offset:55296
	ds_read_b128 v[226:229], v151 offset:56320
	global_load_lds_dwordx4 v[178:179], off
	s_add_i32 m0, s50, 0x2000
	s_add_u32 s48, s48, 0x40080
	v_lshl_add_u64 v[178:179], v[230:231], 0, s[36:37]
	s_addc_u32 s49, s49, 0
	s_add_i32 s50, s55, s20
	global_load_lds_dwordx4 v[178:179], off
	v_lshl_add_u64 v[178:179], s[48:49], 0, v[132:133]
	s_mov_b32 m0, s50
	s_nop 0
	global_load_lds_dwordx4 v[178:179], off
	v_lshl_add_u64 v[178:179], s[48:49], 0, v[128:129]
	s_add_i32 m0, s50, 0x2000
	s_nop 0
	global_load_lds_dwordx4 v[178:179], off
	v_lshl_add_u64 v[178:179], v[232:233], 0, s[36:37]
	s_mov_b32 m0, s25
	s_nop 0
	global_load_lds_dwordx4 v[178:179], off
	v_lshl_add_u64 v[178:179], v[234:235], 0, s[36:37]
	s_mov_b32 m0, s28
	s_nop 0
	global_load_lds_dwordx4 v[178:179], off
	s_waitcnt vmcnt(8)
	s_waitcnt lgkmcnt(0)
	s_barrier
	v_mfma_f32_16x16x32_bf16 v[60:63], v[142:145], v[198:201], v[60:63]
	v_mfma_f32_16x16x32_bf16 v[56:59], v[156:159], v[198:201], v[56:59]
	v_mfma_f32_16x16x32_bf16 v[44:47], v[142:145], v[206:209], v[44:47]
	v_mfma_f32_16x16x32_bf16 v[40:43], v[156:159], v[206:209], v[40:43]
	v_mfma_f32_16x16x32_bf16 v[28:31], v[142:145], v[214:217], v[28:31]
	v_mfma_f32_16x16x32_bf16 v[24:27], v[156:159], v[214:217], v[24:27]
	v_mfma_f32_16x16x32_bf16 v[12:15], v[142:145], v[222:225], v[12:15]
	v_mfma_f32_16x16x32_bf16 v[8:11], v[156:159], v[222:225], v[8:11]
	v_mfma_f32_16x16x32_bf16 v[60:63], v[152:155], v[202:205], v[60:63]
	v_mfma_f32_16x16x32_bf16 v[56:59], v[160:163], v[202:205], v[56:59]
	v_mfma_f32_16x16x32_bf16 v[44:47], v[152:155], v[210:213], v[44:47]
	v_mfma_f32_16x16x32_bf16 v[40:43], v[160:163], v[210:213], v[40:43]
	v_mfma_f32_16x16x32_bf16 v[28:31], v[152:155], v[218:221], v[28:31]
	v_mfma_f32_16x16x32_bf16 v[24:27], v[160:163], v[218:221], v[24:27]
	v_mfma_f32_16x16x32_bf16 v[12:15], v[152:155], v[226:229], v[12:15]
	v_mfma_f32_16x16x32_bf16 v[8:11], v[160:163], v[226:229], v[8:11]
	v_mfma_f32_16x16x32_bf16 v[52:55], v[164:167], v[198:201], v[52:55]
	s_add_i32 s53, s53, 2
	v_mfma_f32_16x16x32_bf16 v[48:51], v[172:175], v[198:201], v[48:51]
	s_add_u32 s41, s41, 0x100
	v_mfma_f32_16x16x32_bf16 v[36:39], v[164:167], v[206:209], v[36:39]
	s_addc_u32 s52, s52, 0
	v_mfma_f32_16x16x32_bf16 v[32:35], v[172:175], v[206:209], v[32:35]
	s_add_u32 s46, s46, 0x100
	v_mfma_f32_16x16x32_bf16 v[20:23], v[164:167], v[214:217], v[20:23]
	s_addc_u32 s47, s47, 0
	v_mfma_f32_16x16x32_bf16 v[16:19], v[172:175], v[214:217], v[16:19]
	s_add_u32 s48, s46, 0xfffc0080
	v_mfma_f32_16x16x32_bf16 v[4:7], v[164:167], v[222:225], v[4:7]
	s_addc_u32 s49, s47, -1
	v_mfma_f32_16x16x32_bf16 v[0:3], v[172:175], v[222:225], v[0:3]
	s_add_i32 s54, 0, 0x10000
	v_mfma_f32_16x16x32_bf16 v[52:55], v[168:171], v[202:205], v[52:55]
	s_cmp_eq_u32 s53, 12
	v_mfma_f32_16x16x32_bf16 v[48:51], v[194:197], v[202:205], v[48:51]
	s_cselect_b32 s51, s33, s49
	v_mfma_f32_16x16x32_bf16 v[36:39], v[168:171], v[210:213], v[36:39]
	s_cselect_b32 s50, s34, s48
	v_mfma_f32_16x16x32_bf16 v[32:35], v[194:197], v[210:213], v[32:35]
	s_cselect_b32 s49, s27, s52
	v_mfma_f32_16x16x32_bf16 v[20:23], v[168:171], v[218:221], v[20:23]
	s_cselect_b32 s48, s35, s41
	v_mfma_f32_16x16x32_bf16 v[16:19], v[194:197], v[218:221], v[16:19]
	s_add_i32 s56, 0, 0x14000
	v_mfma_f32_16x16x32_bf16 v[4:7], v[168:171], v[226:229], v[4:7]
	s_cmp_gt_u32 s53, 13
	v_mfma_f32_16x16x32_bf16 v[0:3], v[194:197], v[226:229], v[0:3]
	s_barrier
	s_nop 3
	v_add_u32_e32 v141, s54, v148
	s_cbranch_scc0 .Lxk_3
	s_and_b64 vcc, exec, s[16:17]
	s_cbranch_vccz .LBB0_662
	s_barrier

; #define PG8_STAGE(bufoff, gbase, voff) do { _Pragma("unroll") for (int _i = 0; _i < 2; ++_i) \
;         __builtin_amdgcn_global_load_lds((const unsigned*)((const char*)(gbase) + (voff)[_i]), (PG8_LAS unsigned*)(lds + (bufoff) + ldsw + _i * 8192), 16, 0, 0); } while (0)
; #define PG8_LDA(dst, b, h) do { _Pragma("unroll") for (int m = 0; m < 4; ++m) _Pragma("unroll") for (int k = 0; k < 2; ++k) dst[m][k] = *(const PG8_LAS bf16x8*)(lds + PG8_SA(b, h) + aoff + m * 2048 + k * 1024); } while (0)
; #define PG8_LDB(dst, b, h) do { _Pragma("unroll") for (int n = 0; n < 2; ++n) _Pragma("unroll") for (int k = 0; k < 2; ++k) dst[n][k] = *(const PG8_LAS bf16x8*)(lds + PG8_SB(b, h) + boff + n * 2048 + k * 1024); } while (0)
; #define PG8_MMA(ai, bj, At, Bt) do { __builtin_amdgcn_s_setprio(1); _Pragma("unroll") for (int m = 0; m < 4; ++m) _Pragma("unroll") for (int n = 0; n < 2; ++n) _Pragma("unroll") for (int k = 0; k < 2; ++k) \
;         acc[ai][bj][m][n] = __builtin_amdgcn_mfma_f32_16x16x32_bf16(Bt[n][k], At[m][k], acc[ai][bj][m][n], 0, 0, 0); __builtin_amdgcn_s_setprio(0); } while (0)
; #define PG8_WAIT_V(n) asm volatile("s_waitcnt vmcnt(" #n ")" ::: "memory")
; #define PG8_BAR __builtin_amdgcn_s_barrier()
; template <class Epi, class Sched, bool ALIGN_EPI = false, bool SP2 = false>
; __device__ __forceinline__ void gemm_phase(PG8_LAS unsigned char* lds, const Gemm g, const Sched& S, const Epi& E) {
;     ...
;         for (int t = 0; t < nt; t += 2) {
;             const bool last = (t == nt - 2);
;             const char* a1 = cA + (size_t)(t + 1) * kstep;
;             const char* a2 = last ? nA : cA + (size_t)(t + 2) * kstep; const char* b2 = last ? nB : cB + (size_t)(t + 2) * kstep;
;             const char* a3 = a2 + kstep; const char* b3 = b2 + kstep;
;             if (last && has_next) S.a_ready(nxt);
;             if constexpr (SP2) {
;             PG8_LDB(B0, 0, 0); PG8_LDB(B1, 0, 1); PG8_SCHED; PG8_LDA(At, 0, 0); PG8_STAGE(PG8_SA(1, 1), a1 + hstep, voffA);
;             PG8_WAIT_V(8); PG8_WAIT_L(0); PG8_BAR; PG8_MMA(0, 0, At, B0); PG8_MMA(0, 1, At, B1); PG8_BAR; PG8_SCHED;
;             PG8_LDA(At, 0, 1); PG8_STAGE(PG8_SB(0, 0), b2, voffB); PG8_STAGE(PG8_SB(0, 1), b2 + hstep, voffB); PG8_STAGE(PG8_SA(0, 0), a2, voffA);
;             PG8_WAIT_V(8); PG8_WAIT_L(0); PG8_BAR; PG8_MMA(1, 0, At, B0); PG8_MMA(1, 1, At, B1); PG8_BAR; PG8_SCHED;
.Lxk_4:
	ds_read_b128 v[120:123], v140
	ds_read_b128 v[132:135], v140 offset:1024
	ds_read_b128 v[136:139], v140 offset:2048
	ds_read_b128 v[140:143], v140 offset:3072
	ds_read_b128 v[144:147], v168
	ds_read_b128 v[148:151], v168 offset:1024
	ds_read_b128 v[152:155], v168 offset:2048
	ds_read_b128 v[168:171], v168 offset:3072
	v_lshl_add_u64 v[178:179], s[4:5], 0, v[166:167]
	s_add_i32 m0, s21, 0xc000
	ds_read_b128 v[172:175], v207
	ds_read_b128 v[194:197], v207 offset:1024
	ds_read_b128 v[198:201], v207 offset:2048
	ds_read_b128 v[208:211], v207 offset:3072
	ds_read_b128 v[212:215], v207 offset:4096
	ds_read_b128 v[216:219], v207 offset:5120
	ds_read_b128 v[220:223], v207 offset:6144
	ds_read_b128 v[224:227], v207 offset:7168
	global_load_lds_dwordx4 v[178:179], off
	v_lshl_add_u64 v[178:179], s[4:5], 0, v[164:165]
	s_add_i32 m0, s21, 0xe000
	s_nop 0
	global_load_lds_dwordx4 v[178:179], off
	s_waitcnt vmcnt(8)
	s_waitcnt lgkmcnt(0)
	s_barrier
	v_mfma_f32_16x16x32_bf16 v[128:131], v[120:123], v[172:175], v[128:131]
	v_mfma_f32_16x16x32_bf16 v[124:127], v[136:139], v[172:175], v[124:127]
	v_mfma_f32_16x16x32_bf16 v[108:111], v[120:123], v[198:201], v[108:111]
	v_mfma_f32_16x16x32_bf16 v[104:107], v[136:139], v[198:201], v[104:107]
	v_mfma_f32_16x16x32_bf16 v[92:95], v[120:123], v[212:215], v[92:95]
	v_mfma_f32_16x16x32_bf16 v[88:91], v[136:139], v[212:215], v[88:91]
	v_mfma_f32_16x16x32_bf16 v[76:79], v[120:123], v[220:223], v[76:79]
	v_mfma_f32_16x16x32_bf16 v[72:75], v[136:139], v[220:223], v[72:75]
	v_mfma_f32_16x16x32_bf16 v[128:131], v[132:135], v[194:197], v[128:131]
	v_mfma_f32_16x16x32_bf16 v[124:127], v[140:143], v[194:197], v[124:127]
	v_mfma_f32_16x16x32_bf16 v[108:111], v[132:135], v[208:211], v[108:111]
	v_mfma_f32_16x16x32_bf16 v[104:107], v[140:143], v[208:211], v[104:107]
	v_mfma_f32_16x16x32_bf16 v[92:95], v[132:135], v[216:219], v[92:95]
	v_mfma_f32_16x16x32_bf16 v[88:91], v[140:143], v[216:219], v[88:91]
	v_mfma_f32_16x16x32_bf16 v[76:79], v[132:135], v[224:227], v[76:79]
	v_mfma_f32_16x16x32_bf16 v[72:75], v[140:143], v[224:227], v[72:75]
	v_mfma_f32_16x16x32_bf16 v[116:119], v[144:147], v[172:175], v[116:119]
	v_mfma_f32_16x16x32_bf16 v[112:115], v[152:155], v[172:175], v[112:115]
	v_mfma_f32_16x16x32_bf16 v[100:103], v[144:147], v[198:201], v[100:103]
	v_mfma_f32_16x16x32_bf16 v[96:99], v[152:155], v[198:201], v[96:99]
	v_mfma_f32_16x16x32_bf16 v[84:87], v[144:147], v[212:215], v[84:87]
	v_mfma_f32_16x16x32_bf16 v[80:83], v[152:155], v[212:215], v[80:83]
	v_mfma_f32_16x16x32_bf16 v[68:71], v[144:147], v[220:223], v[68:71]
	v_mfma_f32_16x16x32_bf16 v[64:67], v[152:155], v[220:223], v[64:67]
	v_mfma_f32_16x16x32_bf16 v[116:119], v[148:151], v[194:197], v[116:119]
	v_mfma_f32_16x16x32_bf16 v[112:115], v[168:171], v[194:197], v[112:115]
	v_mfma_f32_16x16x32_bf16 v[100:103], v[148:151], v[208:211], v[100:103]
	v_mfma_f32_16x16x32_bf16 v[96:99], v[168:171], v[208:211], v[96:99]
	v_mfma_f32_16x16x32_bf16 v[84:87], v[148:151], v[216:219], v[84:87]
	v_mfma_f32_16x16x32_bf16 v[80:83], v[168:171], v[216:219], v[80:83]
	v_mfma_f32_16x16x32_bf16 v[68:71], v[148:151], v[224:227], v[68:71]
	v_mfma_f32_16x16x32_bf16 v[64:67], v[168:171], v[224:227], v[64:67]
	s_barrier
	s_add_i32 s60, s60, s20
	v_lshl_add_u64 v[178:179], s[38:39], 0, v[160:161]
	s_mov_b32 m0, s60
	ds_read_b128 v[172:175], v207 offset:16384
	ds_read_b128 v[194:197], v207 offset:17408
	ds_read_b128 v[198:201], v207 offset:18432
	ds_read_b128 v[208:211], v207 offset:19456
	ds_read_b128 v[212:215], v207 offset:20480
	ds_read_b128 v[216:219], v207 offset:21504
	ds_read_b128 v[220:223], v207 offset:22528
	ds_read_b128 v[224:227], v207 offset:23552
	global_load_lds_dwordx4 v[178:179], off
	s_add_i32 m0, s60, 0x2000
	s_add_u32 s60, s38, 0x100000
	v_lshl_add_u64 v[202:203], s[38:39], 0, v[156:157]
	s_addc_u32 s61, s39, 0
	s_add_i32 s62, s62, s20
	global_load_lds_dwordx4 v[202:203], off
	v_lshl_add_u64 v[228:229], s[60:61], 0, v[160:161]
	s_mov_b32 m0, s62
	v_lshl_add_u64 v[230:231], s[56:57], 0, v[158:159]
	global_load_lds_dwordx4 v[228:229], off
	v_lshl_add_u64 v[228:229], s[60:61], 0, v[156:157]
	s_add_i32 m0, s62, 0x2000
	s_nop 0
	global_load_lds_dwordx4 v[228:229], off
	v_lshl_add_u64 v[228:229], s[56:57], 0, v[162:163]
	s_mov_b32 m0, s21
	s_nop 0
	global_load_lds_dwordx4 v[228:229], off
	s_mov_b32 m0, s22
	s_nop 0
	global_load_lds_dwordx4 v[230:231], off
	s_waitcnt vmcnt(8)
	s_waitcnt lgkmcnt(0)
	s_barrier
	v_mfma_f32_16x16x32_bf16 v[60:63], v[120:123], v[172:175], v[60:63]
	v_mfma_f32_16x16x32_bf16 v[56:59], v[136:139], v[172:175], v[56:59]
	v_mfma_f32_16x16x32_bf16 v[44:47], v[120:123], v[198:201], v[44:47]
	v_mfma_f32_16x16x32_bf16 v[40:43], v[136:139], v[198:201], v[40:43]
	v_mfma_f32_16x16x32_bf16 v[28:31], v[120:123], v[212:215], v[28:31]
	v_mfma_f32_16x16x32_bf16 v[24:27], v[136:139], v[212:215], v[24:27]
	v_mfma_f32_16x16x32_bf16 v[12:15], v[120:123], v[220:223], v[12:15]
	v_mfma_f32_16x16x32_bf16 v[8:11], v[136:139], v[220:223], v[8:11]
	v_mfma_f32_16x16x32_bf16 v[60:63], v[132:135], v[194:197], v[60:63]
	v_mfma_f32_16x16x32_bf16 v[56:59], v[140:143], v[194:197], v[56:59]
	v_mfma_f32_16x16x32_bf16 v[44:47], v[132:135], v[208:211], v[44:47]
	v_mfma_f32_16x16x32_bf16 v[40:43], v[140:143], v[208:211], v[40:43]
	v_mfma_f32_16x16x32_bf16 v[28:31], v[132:135], v[216:219], v[28:31]
	v_mfma_f32_16x16x32_bf16 v[24:27], v[140:143], v[216:219], v[24:27]
	v_mfma_f32_16x16x32_bf16 v[12:15], v[132:135], v[224:227], v[12:15]
	v_mfma_f32_16x16x32_bf16 v[8:11], v[140:143], v[224:227], v[8:11]
	v_mfma_f32_16x16x32_bf16 v[52:55], v[144:147], v[172:175], v[52:55]
	v_mfma_f32_16x16x32_bf16 v[48:51], v[152:155], v[172:175], v[48:51]
	v_mfma_f32_16x16x32_bf16 v[36:39], v[144:147], v[198:201], v[36:39]
	v_mfma_f32_16x16x32_bf16 v[32:35], v[152:155], v[198:201], v[32:35]
	v_mfma_f32_16x16x32_bf16 v[20:23], v[144:147], v[212:215], v[20:23]
	v_mfma_f32_16x16x32_bf16 v[16:19], v[152:155], v[212:215], v[16:19]
	v_mfma_f32_16x16x32_bf16 v[4:7], v[144:147], v[220:223], v[4:7]
	v_mfma_f32_16x16x32_bf16 v[0:3], v[152:155], v[220:223], v[0:3]
	v_mfma_f32_16x16x32_bf16 v[52:55], v[148:151], v[194:197], v[52:55]
	v_mfma_f32_16x16x32_bf16 v[48:51], v[168:171], v[194:197], v[48:51]
	v_mfma_f32_16x16x32_bf16 v[36:39], v[148:151], v[208:211], v[36:39]
	v_mfma_f32_16x16x32_bf16 v[32:35], v[168:171], v[208:211], v[32:35]
	v_mfma_f32_16x16x32_bf16 v[20:23], v[148:151], v[216:219], v[20:23]
	v_mfma_f32_16x16x32_bf16 v[16:19], v[168:171], v[216:219], v[16:19]
	v_mfma_f32_16x16x32_bf16 v[4:7], v[148:151], v[224:227], v[4:7]
	v_mfma_f32_16x16x32_bf16 v[0:3], v[168:171], v[224:227], v[0:3]
	s_barrier
; #define PG8_STAGE(bufoff, gbase, voff) do { _Pragma("unroll") for (int _i = 0; _i < 2; ++_i) \
;         __builtin_amdgcn_global_load_lds((const unsigned*)((const char*)(gbase) + (voff)[_i]), (PG8_LAS unsigned*)(lds + (bufoff) + ldsw + _i * 8192), 16, 0, 0); } while (0)
; #define PG8_LDA(dst, b, h) do { _Pragma("unroll") for (int m = 0; m < 4; ++m) _Pragma("unroll") for (int k = 0; k < 2; ++k) dst[m][k] = *(const PG8_LAS bf16x8*)(lds + PG8_SA(b, h) + aoff + m * 2048 + k * 1024); } while (0)
; #define PG8_LDB(dst, b, h) do { _Pragma("unroll") for (int n = 0; n < 2; ++n) _Pragma("unroll") for (int k = 0; k < 2; ++k) dst[n][k] = *(const PG8_LAS bf16x8*)(lds + PG8_SB(b, h) + boff + n * 2048 + k * 1024); } while (0)
; #define PG8_MMA(ai, bj, At, Bt) do { __builtin_amdgcn_s_setprio(1); _Pragma("unroll") for (int m = 0; m < 4; ++m) _Pragma("unroll") for (int n = 0; n < 2; ++n) _Pragma("unroll") for (int k = 0; k < 2; ++k) \
;         acc[ai][bj][m][n] = __builtin_amdgcn_mfma_f32_16x16x32_bf16(Bt[n][k], At[m][k], acc[ai][bj][m][n], 0, 0, 0); __builtin_amdgcn_s_setprio(0); } while (0)
; #define PG8_WAIT_V(n) asm volatile("s_waitcnt vmcnt(" #n ")" ::: "memory")
; #define PG8_WAIT_L(n) asm volatile("s_waitcnt lgkmcnt(" #n ")" ::: "memory")
; #define PG8_BAR __builtin_amdgcn_s_barrier()
; #define PG8_SCHED __builtin_amdgcn_sched_barrier(0)
; template <class Epi, class Sched, bool ALIGN_EPI = false, bool SP2 = false>
; __device__ __forceinline__ void gemm_phase(PG8_LAS unsigned char* lds, const Gemm g, const Sched& S, const Epi& E) {
;     ...
;             PG8_LDB(B0, 1, 0); PG8_LDB(B1, 1, 1); PG8_SCHED; PG8_LDA(At, 1, 0); PG8_STAGE(PG8_SA(0, 1), a2 + hstep, voffA);
;             PG8_WAIT_V(8); PG8_WAIT_L(0); PG8_BAR; PG8_MMA(0, 0, At, B0); PG8_MMA(0, 1, At, B1); PG8_BAR; PG8_SCHED;
	s_add_i32 s60, 0, 0x18000
	s_add_i32 s61, 0, 0x1c000
	v_add_u32_e32 v140, s60, v205
	v_add_u32_e32 v168, s61, v205
	ds_read_b128 v[120:123], v140
	ds_read_b128 v[132:135], v140 offset:1024
	ds_read_b128 v[136:139], v140 offset:2048
	ds_read_b128 v[140:143], v140 offset:3072
	ds_read_b128 v[144:147], v168
	ds_read_b128 v[148:151], v168 offset:1024
	ds_read_b128 v[152:155], v168 offset:2048
	ds_read_b128 v[168:171], v168 offset:3072
	s_add_u32 s56, s56, 0x100000
	s_addc_u32 s57, s57, 0
	s_mov_b32 m0, s23
	v_lshl_add_u64 v[232:233], s[56:57], 0, v[162:163]
	ds_read_b128 v[172:175], v207 offset:32768
	ds_read_b128 v[194:197], v207 offset:33792
	ds_read_b128 v[198:201], v207 offset:34816
	ds_read_b128 v[208:211], v207 offset:35840
	ds_read_b128 v[212:215], v207 offset:36864
	ds_read_b128 v[216:219], v207 offset:37888
	ds_read_b128 v[220:223], v207 offset:38912
	ds_read_b128 v[224:227], v207 offset:39936
	global_load_lds_dwordx4 v[232:233], off
	v_lshl_add_u64 v[232:233], s[56:57], 0, v[158:159]
	s_mov_b32 m0, s24
	s_nop 0
	global_load_lds_dwordx4 v[232:233], off
	s_waitcnt vmcnt(8)
	s_waitcnt lgkmcnt(0)
	s_barrier
	v_mfma_f32_16x16x32_bf16 v[128:131], v[120:123], v[172:175], v[128:131]
	v_mfma_f32_16x16x32_bf16 v[124:127], v[136:139], v[172:175], v[124:127]
	v_mfma_f32_16x16x32_bf16 v[108:111], v[120:123], v[198:201], v[108:111]
	v_mfma_f32_16x16x32_bf16 v[104:107], v[136:139], v[198:201], v[104:107]
	v_mfma_f32_16x16x32_bf16 v[92:95], v[120:123], v[212:215], v[92:95]
	v_mfma_f32_16x16x32_bf16 v[88:91], v[136:139], v[212:215], v[88:91]
	v_mfma_f32_16x16x32_bf16 v[76:79], v[120:123], v[220:223], v[76:79]
	v_mfma_f32_16x16x32_bf16 v[72:75], v[136:139], v[220:223], v[72:75]
	v_mfma_f32_16x16x32_bf16 v[128:131], v[132:135], v[194:197], v[128:131]
	v_mfma_f32_16x16x32_bf16 v[124:127], v[140:143], v[194:197], v[124:127]
	v_mfma_f32_16x16x32_bf16 v[108:111], v[132:135], v[208:211], v[108:111]
	v_mfma_f32_16x16x32_bf16 v[104:107], v[140:143], v[208:211], v[104:107]
	v_mfma_f32_16x16x32_bf16 v[92:95], v[132:135], v[216:219], v[92:95]
	v_mfma_f32_16x16x32_bf16 v[88:91], v[140:143], v[216:219], v[88:91]
	v_mfma_f32_16x16x32_bf16 v[76:79], v[132:135], v[224:227], v[76:79]
	v_mfma_f32_16x16x32_bf16 v[72:75], v[140:143], v[224:227], v[72:75]
	v_mfma_f32_16x16x32_bf16 v[116:119], v[144:147], v[172:175], v[116:119]
	v_mfma_f32_16x16x32_bf16 v[112:115], v[152:155], v[172:175], v[112:115]
	v_mfma_f32_16x16x32_bf16 v[100:103], v[144:147], v[198:201], v[100:103]
	v_mfma_f32_16x16x32_bf16 v[96:99], v[152:155], v[198:201], v[96:99]
	v_mfma_f32_16x16x32_bf16 v[84:87], v[144:147], v[212:215], v[84:87]
	v_mfma_f32_16x16x32_bf16 v[80:83], v[152:155], v[212:215], v[80:83]
	v_mfma_f32_16x16x32_bf16 v[68:71], v[144:147], v[220:223], v[68:71]
	v_mfma_f32_16x16x32_bf16 v[64:67], v[152:155], v[220:223], v[64:67]
	v_mfma_f32_16x16x32_bf16 v[116:119], v[148:151], v[194:197], v[116:119]
	v_mfma_f32_16x16x32_bf16 v[112:115], v[168:171], v[194:197], v[112:115]
	v_mfma_f32_16x16x32_bf16 v[100:103], v[148:151], v[208:211], v[100:103]
	v_mfma_f32_16x16x32_bf16 v[96:99], v[168:171], v[208:211], v[96:99]
	v_mfma_f32_16x16x32_bf16 v[84:87], v[148:151], v[216:219], v[84:87]
	v_mfma_f32_16x16x32_bf16 v[80:83], v[168:171], v[216:219], v[80:83]
	v_mfma_f32_16x16x32_bf16 v[68:71], v[148:151], v[224:227], v[68:71]
	v_mfma_f32_16x16x32_bf16 v[64:67], v[168:171], v[224:227], v[64:67]
	s_barrier
; #define PG8_STAGE(bufoff, gbase, voff) do { _Pragma("unroll") for (int _i = 0; _i < 2; ++_i) \
;         __builtin_amdgcn_global_load_lds((const unsigned*)((const char*)(gbase) + (voff)[_i]), (PG8_LAS unsigned*)(lds + (bufoff) + ldsw + _i * 8192), 16, 0, 0); } while (0)
; #define PG8_LDA(dst, b, h) do { _Pragma("unroll") for (int m = 0; m < 4; ++m) _Pragma("unroll") for (int k = 0; k < 2; ++k) dst[m][k] = *(const PG8_LAS bf16x8*)(lds + PG8_SA(b, h) + aoff + m * 2048 + k * 1024); } while (0)
; #define PG8_LDB(dst, b, h) do { _Pragma("unroll") for (int n = 0; n < 2; ++n) _Pragma("unroll") for (int k = 0; k < 2; ++k) dst[n][k] = *(const PG8_LAS bf16x8*)(lds + PG8_SB(b, h) + boff + n * 2048 + k * 1024); } while (0)
; #define PG8_BAR __builtin_amdgcn_s_barrier()
; template <class Epi, class Sched, bool ALIGN_EPI = false, bool SP2 = false>
; __device__ __forceinline__ void gemm_phase(PG8_LAS unsigned char* lds, const Gemm g, const Sched& S, const Epi& E) {
;     ...
;             const bool last = (t == nt - 2);
;             const char* a1 = cA + (size_t)(t + 1) * kstep;
;             const char* a2 = last ? nA : cA + (size_t)(t + 2) * kstep; const char* b2 = last ? nB : cB + (size_t)(t + 2) * kstep;
;             const char* a3 = a2 + kstep; const char* b3 = b2 + kstep;
;             if (last && has_next) S.a_ready(nxt);
;             if constexpr (SP2) {
;             PG8_LDB(B0, 0, 0); PG8_LDB(B1, 0, 1); PG8_SCHED; PG8_LDA(At, 0, 0); PG8_STAGE(PG8_SA(1, 1), a1 + hstep, voffA);
;             PG8_WAIT_V(8); PG8_WAIT_L(0); PG8_BAR; PG8_MMA(0, 0, At, B0); PG8_MMA(0, 1, At, B1); PG8_BAR; PG8_SCHED;
;             PG8_LDA(At, 0, 1); PG8_STAGE(PG8_SB(0, 0), b2, voffB); PG8_STAGE(PG8_SB(0, 1), b2 + hstep, voffB); PG8_STAGE(PG8_SA(0, 0), a2, voffA);
;             PG8_WAIT_V(8); PG8_WAIT_L(0); PG8_BAR; PG8_MMA(1, 0, At, B0); PG8_MMA(1, 1, At, B1); PG8_BAR; PG8_SCHED;
;             PG8_LDB(B0, 1, 0); PG8_LDB(B1, 1, 1); PG8_SCHED; PG8_LDA(At, 1, 0); PG8_STAGE(PG8_SA(0, 1), a2 + hstep, voffA);
;             PG8_WAIT_V(8); PG8_WAIT_L(0); PG8_BAR; PG8_MMA(0, 0, At, B0); PG8_MMA(0, 1, At, B1); PG8_BAR; PG8_SCHED;
;             PG8_LDA(At, 1, 1); PG8_STAGE(PG8_SB(1, 0), b3, voffB); PG8_STAGE(PG8_SB(1, 1), b3 + hstep, voffB); PG8_STAGE(PG8_SA(1, 0), a3, voffA);
;             PG8_WAIT_V(8); PG8_WAIT_L(0); PG8_BAR; PG8_MMA(1, 0, At, B0); PG8_MMA(1, 1, At, B1); PG8_BAR; PG8_SCHED;
	s_add_i32 s56, s60, s20
	v_lshl_add_u64 v[178:179], v[178:179], 0, s[36:37]
	s_mov_b32 m0, s56
	ds_read_b128 v[172:175], v207 offset:49152
	ds_read_b128 v[194:197], v207 offset:50176
	ds_read_b128 v[198:201], v207 offset:51200
	ds_read_b128 v[208:211], v207 offset:52224
	ds_read_b128 v[212:215], v207 offset:53248
	ds_read_b128 v[216:219], v207 offset:54272
	ds_read_b128 v[220:223], v207 offset:55296
	ds_read_b128 v[224:227], v207 offset:56320
	global_load_lds_dwordx4 v[178:179], off
	s_add_i32 m0, s56, 0x2000
	s_add_u32 s38, s38, 0x100080
	v_lshl_add_u64 v[178:179], v[202:203], 0, s[36:37]
	s_addc_u32 s39, s39, 0
	s_add_i32 s56, s61, s20
	global_load_lds_dwordx4 v[178:179], off
	v_lshl_add_u64 v[178:179], s[38:39], 0, v[160:161]
	s_mov_b32 m0, s56
	s_nop 0
	global_load_lds_dwordx4 v[178:179], off
	v_lshl_add_u64 v[178:179], s[38:39], 0, v[156:157]
	s_add_i32 m0, s56, 0x2000
	s_nop 0
	global_load_lds_dwordx4 v[178:179], off
	v_lshl_add_u64 v[178:179], v[228:229], 0, s[36:37]
	s_mov_b32 m0, s29
	s_nop 0
	global_load_lds_dwordx4 v[178:179], off
	v_lshl_add_u64 v[178:179], v[230:231], 0, s[36:37]
	s_mov_b32 m0, s30
	s_nop 0
	global_load_lds_dwordx4 v[178:179], off
	s_waitcnt vmcnt(8)
	s_waitcnt lgkmcnt(0)
	s_barrier
	v_mfma_f32_16x16x32_bf16 v[60:63], v[120:123], v[172:175], v[60:63]
	v_mfma_f32_16x16x32_bf16 v[56:59], v[136:139], v[172:175], v[56:59]
	v_mfma_f32_16x16x32_bf16 v[44:47], v[120:123], v[198:201], v[44:47]
	v_mfma_f32_16x16x32_bf16 v[40:43], v[136:139], v[198:201], v[40:43]
	v_mfma_f32_16x16x32_bf16 v[28:31], v[120:123], v[212:215], v[28:31]
	v_mfma_f32_16x16x32_bf16 v[24:27], v[136:139], v[212:215], v[24:27]
	v_mfma_f32_16x16x32_bf16 v[12:15], v[120:123], v[220:223], v[12:15]
	v_mfma_f32_16x16x32_bf16 v[8:11], v[136:139], v[220:223], v[8:11]
	v_mfma_f32_16x16x32_bf16 v[60:63], v[132:135], v[194:197], v[60:63]
	v_mfma_f32_16x16x32_bf16 v[56:59], v[140:143], v[194:197], v[56:59]
	v_mfma_f32_16x16x32_bf16 v[44:47], v[132:135], v[208:211], v[44:47]
	v_mfma_f32_16x16x32_bf16 v[40:43], v[140:143], v[208:211], v[40:43]
	v_mfma_f32_16x16x32_bf16 v[28:31], v[132:135], v[216:219], v[28:31]
	v_mfma_f32_16x16x32_bf16 v[24:27], v[140:143], v[216:219], v[24:27]
	v_mfma_f32_16x16x32_bf16 v[12:15], v[132:135], v[224:227], v[12:15]
	v_mfma_f32_16x16x32_bf16 v[8:11], v[140:143], v[224:227], v[8:11]
	v_mfma_f32_16x16x32_bf16 v[52:55], v[144:147], v[172:175], v[52:55]
	s_add_i32 s59, s59, 2
	v_mfma_f32_16x16x32_bf16 v[48:51], v[152:155], v[172:175], v[48:51]
	s_add_u32 s51, s51, 0x100
	v_mfma_f32_16x16x32_bf16 v[36:39], v[144:147], v[198:201], v[36:39]
	s_addc_u32 s58, s58, 0
	v_mfma_f32_16x16x32_bf16 v[32:35], v[152:155], v[198:201], v[32:35]
	s_add_u32 s4, s4, 0x100
	v_mfma_f32_16x16x32_bf16 v[20:23], v[144:147], v[212:215], v[20:23]
	s_addc_u32 s5, s5, 0
	v_mfma_f32_16x16x32_bf16 v[16:19], v[152:155], v[212:215], v[16:19]
	s_add_u32 s38, s4, 0xfff00080
	v_mfma_f32_16x16x32_bf16 v[4:7], v[144:147], v[220:223], v[4:7]
	s_addc_u32 s39, s5, -1
	v_mfma_f32_16x16x32_bf16 v[0:3], v[152:155], v[220:223], v[0:3]
	s_add_i32 s60, 0, 0x10000
	v_mfma_f32_16x16x32_bf16 v[52:55], v[148:151], v[194:197], v[52:55]
	s_cmp_eq_u32 s59, 60
	v_mfma_f32_16x16x32_bf16 v[48:51], v[168:171], v[194:197], v[48:51]
	s_cselect_b32 s57, s33, s39
	v_mfma_f32_16x16x32_bf16 v[36:39], v[148:151], v[208:211], v[36:39]
	s_cselect_b32 s56, s34, s38
	v_mfma_f32_16x16x32_bf16 v[32:35], v[168:171], v[208:211], v[32:35]
	s_cselect_b32 s39, s35, s58
	v_mfma_f32_16x16x32_bf16 v[20:23], v[148:151], v[216:219], v[20:23]
	s_cselect_b32 s38, s49, s51
	v_mfma_f32_16x16x32_bf16 v[16:19], v[168:171], v[216:219], v[16:19]
	s_add_i32 s62, 0, 0x14000
	v_mfma_f32_16x16x32_bf16 v[4:7], v[148:151], v[224:227], v[4:7]
	s_cmp_gt_u32 s59, 61
	v_mfma_f32_16x16x32_bf16 v[0:3], v[168:171], v[224:227], v[0:3]
	s_barrier
	s_nop 3
	v_add_u32_e32 v140, s60, v205
	v_add_u32_e32 v168, s62, v205
	s_cbranch_scc0 .Lxk_4
	s_and_b64 vcc, exec, s[42:43]
	s_cbranch_vccz .LBB0_747
	s_barrier
